# mixer epilogues: pair row-per-lane dwordx2 stores into dwordx4 via v_permlane16_swap (36 pairs: norm_store x3, q, rotary k)
# speedup vs baseline: 1.0164x; 1.0164x over previous
; #define LAS __attribute__((address_space(3)))
; __device__ __forceinline__ unsigned pk2(float lo, float hi) { unsigned r; asm("v_cvt_pk_bf16_f32 %0, %1, %2" : "=v"(r) : "v"(lo), "v"(hi)); return r; }
; __device__ __forceinline__ float rsq(float x) { return __builtin_amdgcn_rsqf(x); }
; template <int NNT>
; __device__ __forceinline__ void norm_store(const f32x4 (&acc)[8][NNT], const LAS float* part, bf16_t* dst, int fr) {
; #pragma unroll
;     for (int mt = 0; mt < 8; ++mt) {
;         const LAS f32x4* pp = (const LAS f32x4*)(part + (16 * mt + fr) * 8); const f32x4 a = pp[0], b = pp[1];
;         const float rs = rsq((((a[0] + a[1]) + (a[2] + a[3])) + ((b[0] + b[1]) + (b[2] + b[3]))) * (1.0f / 256.0f) + EPS);
; #pragma unroll
;         for (int nt = 0; nt < NNT; ++nt) { u32x2 o; o.x = pk2(acc[mt][nt][0] * rs, acc[mt][nt][1] * rs); o.y = pk2(acc[mt][nt][2] * rs, acc[mt][nt][3] * rs);
;             *(u32x2*)(dst + (size_t)(16 * mt) * DM + 16 * nt) = o; }
;     }
; }
; __device__ __forceinline__ void mixer_chunk(KP p, LAS unsigned char* lds, int l, int chunk) {
;     ...
;         part_sumsq<2>(acc, part0, w, fr, fq);
;         __syncthreads();
;         norm_store<2>(acc, part0, mrow + 768 + 64 * h + 16 * t0, fr);
;     }
;     __syncthreads();
.LBB0_281:
	s_or_b64 exec, exec, s[6:7]
	s_waitcnt lgkmcnt(0)
	s_barrier
	ds_read_b128 v[18:21], v215
	ds_read_b128 v[34:37], v215 offset:16
	s_add_i32 s23, s23, s52
	s_cmpk_gt_i32 s23, 0xff
	s_waitcnt lgkmcnt(1)
	v_mov_b32_e32 v38, v18
	s_waitcnt lgkmcnt(0)
	v_mov_b32_e32 v39, v34
	v_mov_b32_e32 v34, v19
	v_pk_add_f32 v[18:19], v[38:39], v[34:35]
	v_mov_b32_e32 v34, v20
	v_mov_b32_e32 v35, v36
	v_mov_b32_e32 v36, v21
	v_pk_add_f32 v[20:21], v[34:35], v[36:37]
	s_nop 0
	v_pk_add_f32 v[18:19], v[18:19], v[20:21]
	s_nop 0
	v_add_f32_e32 v18, v18, v19
	v_fmamk_f32 v18, v18, 0x3b800000, v189
	v_rsq_f32_e32 v20, v18
	s_nop 0
	v_mul_f32_e32 v0, v0, v20
	v_mul_f32_e32 v18, v135, v20
	v_mul_f32_e32 v19, v137, v20
	v_cvt_pk_bf16_f32 v18, v0, v18
	v_mul_f32_e32 v0, v136, v20
	v_cvt_pk_bf16_f32 v19, v0, v19
	s_nop 1
	v_mov_b32_e32 v244, v18
	v_mov_b32_e32 v245, v19
	v_mul_f32_e32 v0, v138, v20
	v_mul_f32_e32 v18, v139, v20
	v_mul_f32_e32 v19, v141, v20
	v_cvt_pk_bf16_f32 v18, v0, v18
	v_mul_f32_e32 v0, v140, v20
	v_cvt_pk_bf16_f32 v19, v0, v19
	v_mov_b32_e32 v246, v18
	v_mov_b32_e32 v247, v19
	v_bfe_u32 v248, v193, 4, 1
	v_mul_u32_u24_e32 v248, 24, v248
	v_add_co_u32_e64 v248, s[98:99], v248, v82
	s_nop 1
	v_addc_co_u32_e64 v249, s[98:99], 0, v83, s[98:99]
	v_permlane16_swap_b32_e32 v244, v246
	v_permlane16_swap_b32_e32 v245, v247
	global_store_dwordx4 v[248:249], v[244:247], off offset:1536
	ds_read_b128 v[18:21], v215 offset:512
	ds_read_b128 v[34:37], v215 offset:528
	s_waitcnt lgkmcnt(1)
	v_mov_b32_e32 v38, v18
	s_waitcnt lgkmcnt(0)
	v_mov_b32_e32 v39, v34
	v_mov_b32_e32 v34, v19
	v_pk_add_f32 v[18:19], v[38:39], v[34:35]
	v_mov_b32_e32 v34, v20
	v_mov_b32_e32 v35, v36
	v_mov_b32_e32 v36, v21
	v_pk_add_f32 v[20:21], v[34:35], v[36:37]
	s_nop 0
	v_pk_add_f32 v[18:19], v[18:19], v[20:21]
	s_nop 0
	v_add_f32_e32 v0, v18, v19
	v_fmamk_f32 v0, v0, 0x3b800000, v189
	v_rsq_f32_e32 v0, v0
	s_nop 0
	v_mul_f32_e32 v18, v126, v0
	v_mul_f32_e32 v19, v124, v0
	v_cvt_pk_bf16_f32 v18, v18, v19
	v_mul_f32_e32 v19, v127, v0
	v_mul_f32_e32 v20, v125, v0
	v_cvt_pk_bf16_f32 v19, v19, v20
	s_nop 1
	v_mov_b32_e32 v244, v18
	v_mov_b32_e32 v245, v19
	v_mul_f32_e32 v18, v76, v0
	v_mul_f32_e32 v19, v77, v0
	v_cvt_pk_bf16_f32 v18, v18, v19
	v_mul_f32_e32 v19, v122, v0
	v_mul_f32_e32 v0, v123, v0
	v_cvt_pk_bf16_f32 v19, v19, v0
	v_mov_b32_e32 v246, v18
	v_mov_b32_e32 v247, v19
	v_bfe_u32 v248, v193, 4, 1
	v_mul_u32_u24_e32 v248, 24, v248
	v_add_co_u32_e64 v248, s[98:99], v248, v84
	s_nop 1
	v_addc_co_u32_e64 v249, s[98:99], 0, v85, s[98:99]
	v_permlane16_swap_b32_e32 v244, v246
	v_permlane16_swap_b32_e32 v245, v247
	global_store_dwordx4 v[248:249], v[244:247], off offset:1536
	ds_read_b128 v[18:21], v215 offset:1024
	ds_read_b128 v[34:37], v215 offset:1040
	s_waitcnt lgkmcnt(1)
	v_mov_b32_e32 v38, v18
	s_waitcnt lgkmcnt(0)
	v_mov_b32_e32 v39, v34
	v_mov_b32_e32 v34, v19
	v_pk_add_f32 v[18:19], v[38:39], v[34:35]
	v_mov_b32_e32 v34, v20
	v_mov_b32_e32 v35, v36
	v_mov_b32_e32 v36, v21
	v_pk_add_f32 v[20:21], v[34:35], v[36:37]
	s_nop 0
	v_pk_add_f32 v[18:19], v[18:19], v[20:21]
	s_nop 0
	v_add_f32_e32 v0, v18, v19
	v_fmamk_f32 v0, v0, 0x3b800000, v189
	v_rsq_f32_e32 v0, v0
	s_nop 0
	v_mul_f32_e32 v18, v67, v0
	v_mul_f32_e32 v19, v69, v0
	v_cvt_pk_bf16_f32 v18, v18, v19
	v_mul_f32_e32 v19, v74, v0
	v_mul_f32_e32 v20, v75, v0
	v_cvt_pk_bf16_f32 v19, v19, v20
	s_nop 1
	v_mov_b32_e32 v244, v18
	v_mov_b32_e32 v245, v19
	v_mul_f32_e32 v18, v68, v0
	v_mul_f32_e32 v19, v70, v0
	v_cvt_pk_bf16_f32 v18, v18, v19
	v_mul_f32_e32 v19, v71, v0
	v_mul_f32_e32 v0, v72, v0
	v_cvt_pk_bf16_f32 v19, v19, v0
	v_mov_b32_e32 v246, v18
	v_mov_b32_e32 v247, v19
	v_bfe_u32 v248, v193, 4, 1
	v_mul_u32_u24_e32 v248, 24, v248
	v_add_co_u32_e64 v248, s[98:99], v248, v86
	s_nop 1
	v_addc_co_u32_e64 v249, s[98:99], 0, v87, s[98:99]
	v_permlane16_swap_b32_e32 v244, v246
	v_permlane16_swap_b32_e32 v245, v247
	global_store_dwordx4 v[248:249], v[244:247], off offset:1536
	ds_read_b128 v[18:21], v215 offset:1536
	ds_read_b128 v[34:37], v215 offset:1552
	s_waitcnt lgkmcnt(1)
	v_mov_b32_e32 v38, v18
	s_waitcnt lgkmcnt(0)
	v_mov_b32_e32 v39, v34
	v_mov_b32_e32 v34, v19
	v_pk_add_f32 v[18:19], v[38:39], v[34:35]
	v_mov_b32_e32 v34, v20
	v_mov_b32_e32 v35, v36
	v_mov_b32_e32 v36, v21
	v_pk_add_f32 v[20:21], v[34:35], v[36:37]
	s_nop 0
	v_pk_add_f32 v[18:19], v[18:19], v[20:21]
	s_nop 0
	v_add_f32_e32 v0, v18, v19
	v_fmamk_f32 v0, v0, 0x3b800000, v189
	v_rsq_f32_e32 v0, v0
	s_nop 0
	v_mul_f32_e32 v18, v62, v0
	v_mul_f32_e32 v19, v66, v0
	v_cvt_pk_bf16_f32 v18, v18, v19
	v_mul_f32_e32 v19, v64, v0
	v_mul_f32_e32 v20, v65, v0
	v_cvt_pk_bf16_f32 v19, v19, v20
	s_nop 1
	v_mov_b32_e32 v244, v18
	v_mov_b32_e32 v245, v19
	v_mul_f32_e32 v18, v63, v0
	v_mul_f32_e32 v19, v55, v0
	v_cvt_pk_bf16_f32 v18, v18, v19
	v_mul_f32_e32 v19, v56, v0
	v_mul_f32_e32 v0, v57, v0
	v_cvt_pk_bf16_f32 v19, v19, v0
	v_mov_b32_e32 v246, v18
	v_mov_b32_e32 v247, v19
	v_bfe_u32 v248, v193, 4, 1
	v_mul_u32_u24_e32 v248, 24, v248
	v_add_co_u32_e64 v248, s[98:99], v248, v88
	s_nop 1
	v_addc_co_u32_e64 v249, s[98:99], 0, v89, s[98:99]
	v_permlane16_swap_b32_e32 v244, v246
	v_permlane16_swap_b32_e32 v245, v247
	global_store_dwordx4 v[248:249], v[244:247], off offset:1536
	ds_read_b128 v[18:21], v215 offset:2048
	ds_read_b128 v[34:37], v215 offset:2064
	s_waitcnt lgkmcnt(1)
; #define LAS __attribute__((address_space(3)))
; __device__ __forceinline__ unsigned pk2(float lo, float hi) { unsigned r; asm("v_cvt_pk_bf16_f32 %0, %1, %2" : "=v"(r) : "v"(lo), "v"(hi)); return r; }
; __device__ __forceinline__ float rsq(float x) { return __builtin_amdgcn_rsqf(x); }
; template <int NNT>
; __device__ __forceinline__ void norm_store(const f32x4 (&acc)[8][NNT], const LAS float* part, bf16_t* dst, int fr) {
; #pragma unroll
;     for (int mt = 0; mt < 8; ++mt) {
;         const LAS f32x4* pp = (const LAS f32x4*)(part + (16 * mt + fr) * 8); const f32x4 a = pp[0], b = pp[1];
;         const float rs = rsq((((a[0] + a[1]) + (a[2] + a[3])) + ((b[0] + b[1]) + (b[2] + b[3]))) * (1.0f / 256.0f) + EPS);
; #pragma unroll
;         for (int nt = 0; nt < NNT; ++nt) { u32x2 o; o.x = pk2(acc[mt][nt][0] * rs, acc[mt][nt][1] * rs); o.y = pk2(acc[mt][nt][2] * rs, acc[mt][nt][3] * rs);
;             *(u32x2*)(dst + (size_t)(16 * mt) * DM + 16 * nt) = o; }
;     }
; }
; __device__ __forceinline__ void mixer_chunk(KP p, LAS unsigned char* lds, int l, int chunk) {
;     ...
;         part_sumsq<2>(acc, part0, w, fr, fq);
;         __syncthreads();
;         norm_store<2>(acc, part0, mrow + 768 + 64 * h + 16 * t0, fr);
;     }
;     __syncthreads();
	v_mov_b32_e32 v38, v18
	s_waitcnt lgkmcnt(0)
	v_mov_b32_e32 v39, v34
	v_mov_b32_e32 v34, v19
	v_pk_add_f32 v[18:19], v[38:39], v[34:35]
	v_mov_b32_e32 v34, v20
	v_mov_b32_e32 v35, v36
	v_mov_b32_e32 v36, v21
	v_pk_add_f32 v[20:21], v[34:35], v[36:37]
	s_nop 0
	v_pk_add_f32 v[18:19], v[18:19], v[20:21]
	s_nop 0
	v_add_f32_e32 v0, v18, v19
	v_fmamk_f32 v0, v0, 0x3b800000, v189
	v_rsq_f32_e32 v0, v0
	s_nop 0
	v_mul_f32_e32 v18, v30, v0
	v_mul_f32_e32 v19, v32, v0
	v_cvt_pk_bf16_f32 v18, v18, v19
	v_mul_f32_e32 v19, v33, v0
	v_mul_f32_e32 v20, v54, v0
	v_cvt_pk_bf16_f32 v19, v19, v20
	s_nop 1
	v_mov_b32_e32 v244, v18
	v_mov_b32_e32 v245, v19
	v_mul_f32_e32 v18, v31, v0
	v_mul_f32_e32 v19, v50, v0
	v_cvt_pk_bf16_f32 v18, v18, v19
	v_mul_f32_e32 v19, v51, v0
	v_mul_f32_e32 v0, v52, v0
	v_cvt_pk_bf16_f32 v19, v19, v0
	v_mov_b32_e32 v246, v18
	v_mov_b32_e32 v247, v19
	v_bfe_u32 v248, v193, 4, 1
	v_mul_u32_u24_e32 v248, 24, v248
	v_add_co_u32_e64 v248, s[98:99], v248, v90
	s_nop 1
	v_addc_co_u32_e64 v249, s[98:99], 0, v91, s[98:99]
	v_permlane16_swap_b32_e32 v244, v246
	v_permlane16_swap_b32_e32 v245, v247
	global_store_dwordx4 v[248:249], v[244:247], off offset:1536
	ds_read_b128 v[18:21], v215 offset:2560
	ds_read_b128 v[30:33], v215 offset:2576
	s_waitcnt lgkmcnt(1)
	v_mov_b32_e32 v34, v18
	s_waitcnt lgkmcnt(0)
	v_mov_b32_e32 v35, v30
	v_mov_b32_e32 v30, v19
	v_pk_add_f32 v[18:19], v[34:35], v[30:31]
	v_mov_b32_e32 v30, v20
	v_mov_b32_e32 v31, v32
	v_mov_b32_e32 v32, v21
	v_pk_add_f32 v[20:21], v[30:31], v[32:33]
	s_nop 0
	v_pk_add_f32 v[18:19], v[18:19], v[20:21]
	s_nop 0
	v_add_f32_e32 v0, v18, v19
	v_fmamk_f32 v0, v0, 0x3b800000, v189
	v_rsq_f32_e32 v0, v0
	s_nop 0
	v_mul_f32_e32 v18, v22, v0
	v_mul_f32_e32 v19, v24, v0
	v_cvt_pk_bf16_f32 v18, v18, v19
	v_mul_f32_e32 v19, v25, v0
	v_mul_f32_e32 v20, v28, v0
	v_cvt_pk_bf16_f32 v19, v19, v20
	s_nop 1
	v_mov_b32_e32 v244, v18
	v_mov_b32_e32 v245, v19
	v_mul_f32_e32 v18, v23, v0
	v_mul_f32_e32 v19, v26, v0
	v_cvt_pk_bf16_f32 v18, v18, v19
	v_mul_f32_e32 v19, v27, v0
	v_mul_f32_e32 v0, v29, v0
	v_cvt_pk_bf16_f32 v19, v19, v0
	v_mov_b32_e32 v246, v18
	v_mov_b32_e32 v247, v19
	v_bfe_u32 v248, v193, 4, 1
	v_mul_u32_u24_e32 v248, 24, v248
	v_add_co_u32_e64 v248, s[98:99], v248, v92
	s_nop 1
	v_addc_co_u32_e64 v249, s[98:99], 0, v93, s[98:99]
	v_permlane16_swap_b32_e32 v244, v246
	v_permlane16_swap_b32_e32 v245, v247
	global_store_dwordx4 v[248:249], v[244:247], off offset:1536
	ds_read_b128 v[18:21], v215 offset:3072
	ds_read_b128 v[22:25], v215 offset:3088
	s_waitcnt lgkmcnt(1)
	v_mov_b32_e32 v26, v18
	s_waitcnt lgkmcnt(0)
	v_mov_b32_e32 v27, v22
	v_mov_b32_e32 v22, v19
	v_pk_add_f32 v[18:19], v[26:27], v[22:23]
	v_mov_b32_e32 v22, v20
	v_mov_b32_e32 v23, v24
	v_mov_b32_e32 v24, v21
	v_pk_add_f32 v[20:21], v[22:23], v[24:25]
	s_nop 0
	v_pk_add_f32 v[18:19], v[18:19], v[20:21]
	s_nop 0
	v_add_f32_e32 v0, v18, v19
	v_fmamk_f32 v0, v0, 0x3b800000, v189
	v_rsq_f32_e32 v0, v0
	s_nop 0
	v_mul_f32_e32 v10, v10, v0
	v_mul_f32_e32 v12, v12, v0
	v_cvt_pk_bf16_f32 v12, v10, v12
	v_mul_f32_e32 v10, v13, v0
	v_mul_f32_e32 v13, v16, v0
	v_cvt_pk_bf16_f32 v13, v10, v13
	v_mul_f32_e32 v10, v11, v0
	v_mul_f32_e32 v11, v14, v0
	v_cvt_pk_bf16_f32 v10, v10, v11
	v_mul_f32_e32 v11, v15, v0
	s_nop 1
	v_mov_b32_e32 v244, v12
	v_mov_b32_e32 v245, v13
	v_mul_f32_e32 v0, v17, v0
	v_cvt_pk_bf16_f32 v11, v11, v0
	v_mov_b32_e32 v246, v10
	v_mov_b32_e32 v247, v11
	v_bfe_u32 v248, v193, 4, 1
	v_mul_u32_u24_e32 v248, 24, v248
	v_add_co_u32_e64 v248, s[98:99], v248, v94
	s_nop 1
	v_addc_co_u32_e64 v249, s[98:99], 0, v95, s[98:99]
	v_permlane16_swap_b32_e32 v244, v246
	v_permlane16_swap_b32_e32 v245, v247
	global_store_dwordx4 v[248:249], v[244:247], off offset:1536
	ds_read_b128 v[10:13], v215 offset:3584
	ds_read_b128 v[14:17], v215 offset:3600
	s_waitcnt lgkmcnt(1)
	v_mov_b32_e32 v18, v10
	s_waitcnt lgkmcnt(0)
	v_mov_b32_e32 v19, v14
	v_mov_b32_e32 v14, v11
	v_pk_add_f32 v[10:11], v[18:19], v[14:15]
	v_mov_b32_e32 v14, v12
	v_mov_b32_e32 v15, v16
	v_mov_b32_e32 v16, v13
	v_pk_add_f32 v[12:13], v[14:15], v[16:17]
	s_nop 0
	v_pk_add_f32 v[10:11], v[10:11], v[12:13]
	s_nop 0
	v_add_f32_e32 v0, v10, v11
	v_fmamk_f32 v0, v0, 0x3b800000, v189
	v_rsq_f32_e32 v0, v0
	s_nop 0
	v_mul_f32_e32 v6, v6, v0
	v_mul_f32_e32 v7, v7, v0
	v_mul_f32_e32 v2, v2, v0
	v_mul_f32_e32 v3, v3, v0
	v_cvt_pk_bf16_f32 v6, v6, v7
	v_mul_f32_e32 v7, v8, v0
	v_cvt_pk_bf16_f32 v2, v2, v3
	v_mul_f32_e32 v3, v4, v0
	v_mul_f32_e32 v8, v9, v0
	v_cvt_pk_bf16_f32 v7, v7, v8
	s_nop 1
	v_mov_b32_e32 v244, v6
	v_mov_b32_e32 v245, v7
	v_mul_f32_e32 v0, v5, v0
	v_cvt_pk_bf16_f32 v3, v3, v0
	v_mov_b32_e32 v246, v2
	v_mov_b32_e32 v247, v3
	v_bfe_u32 v248, v193, 4, 1
	v_mul_u32_u24_e32 v248, 24, v248
	v_add_co_u32_e64 v248, s[98:99], v248, v96
	s_nop 1
	v_addc_co_u32_e64 v249, s[98:99], 0, v97, s[98:99]
	v_permlane16_swap_b32_e32 v244, v246
	v_permlane16_swap_b32_e32 v245, v247
	global_store_dwordx4 v[248:249], v[244:247], off offset:1536
	s_barrier
	s_cbranch_scc1 .LBB0_434

; __device__ __forceinline__ unsigned pk2(float lo, float hi) { unsigned r; asm("v_cvt_pk_bf16_f32 %0, %1, %2" : "=v"(r) : "v"(lo), "v"(hi)); return r; }
; __device__ __forceinline__ float bf_lo(unsigned w) { return __uint_as_float(w << 16); }
; __device__ __forceinline__ float bf_hi(unsigned w) { return __uint_as_float(w & 0xffff0000u); }
; __device__ __forceinline__ void mixer_chunk(KP p, LAS unsigned char* lds, int l, int chunk) {
;     ...
;         const int row = c0 + 16 * w + fr, spos = s0 + 16 * w + fr;
;         const bf16_t* zr = zb + (size_t)row * DIN_P; const float* rt = (const float*)(ws + OFF_ROPE) + (size_t)row * 32;
;         const u32x2 r1 = *(const u32x2*)(zr + ZC_KR + 4 * fq), r2 = *(const u32x2*)(zr + ZC_KR + 16 + 4 * fq);
;         const f32x4 cs = *(const f32x4*)(rt + 4 * fq), sn = *(const f32x4*)(rt + 16 + 4 * fq);
;         const f32x4 k1 = (f32x4){bf_lo(r1.x), bf_hi(r1.x), bf_lo(r1.y), bf_hi(r1.y)}, k2 = (f32x4){bf_lo(r2.x), bf_hi(r2.x), bf_lo(r2.y), bf_hi(r2.y)};
;         const f32x4 o1 = k1 * cs - k2 * sn, o2 = k2 * cs + k1 * sn;
;         u32x2 ro1, ro2; ro1.x = pk2(o1[0], o1[1]); ro1.y = pk2(o1[2], o1[3]); ro2.x = pk2(o2[0], o2[1]); ro2.y = pk2(o2[2], o2[3]);
;         bf16_t* kd = (bf16_t*)(ws + OFF_K) + ((size_t)(bidx * 4) * SEQ + spos) * 96 + 64 + 4 * fq;
; #pragma unroll
;         for (int h = 0; h < 4; ++h) { *(u32x2*)(kd + (size_t)h * SEQ * 96) = ro1; *(u32x2*)(kd + (size_t)h * SEQ * 96 + 16) = ro2; }
;     }
;     __syncthreads();
.LBB0_316:
	s_or_b64 exec, exec, s[6:7]
	v_or_b32_e32 v168, s25, v217
	v_ashrrev_i32_e32 v169, 31, v168
	v_readlane_b32 s6, v252, 6
	v_lshlrev_b64 v[70:71], 11, v[168:169]
	v_readlane_b32 s7, v252, 7
	v_mov_b32_e32 v67, v1
	s_add_i32 s89, s88, s25
	v_lshl_add_u64 v[70:71], s[6:7], 0, v[70:71]
	v_lshl_add_u64 v[170:171], v[70:71], 0, v[66:67]
	v_or_b32_e32 v70, s89, v217
	s_add_i32 s6, s88, s24
	v_ashrrev_i32_e32 v71, 31, v70
	s_waitcnt lgkmcnt(0)
	v_mov_b64_e32 v[72:73], s[44:45]
	v_or_b32_e32 v76, s6, v217
	v_mad_i64_i32 v[72:73], s[6:7], v70, s65, v[72:73]
	v_lshlrev_b64 v[70:71], 7, v[70:71]
	v_lshlrev_b32_e32 v221, 2, v68
	v_lshl_add_u64 v[70:71], s[92:93], 0, v[70:71]
	v_lshl_add_u64 v[72:73], v[72:73], 0, v[66:67]
	v_lshlrev_b32_e32 v68, 4, v68
	v_mov_b32_e32 v69, v1
	global_load_dwordx2 v[78:79], v[72:73], off offset:1664
	global_load_dwordx2 v[80:81], v[72:73], off offset:1696
	v_lshl_add_u64 v[72:73], v[70:71], 0, v[68:69]
	global_load_dwordx4 v[68:71], v[72:73], off
	s_nop 0
	global_load_dwordx4 v[72:75], v[72:73], off offset:64
	s_ashr_i32 s6, s23, 3
	s_and_b32 s96, s6, -4
	s_ashr_i32 s97, s96, 31
	s_lshl_b64 s[6:7], s[96:97], 12
	v_ashrrev_i32_e32 v77, 31, v76
	s_ashr_i32 s43, s42, 31
	s_cmp_eq_u32 s46, 0
	s_waitcnt vmcnt(3)
	v_lshlrev_b32_e32 v82, 16, v78
	s_waitcnt vmcnt(2)
	v_lshlrev_b32_e32 v84, 16, v80
	v_and_b32_e32 v85, 0xffff0000, v80
	v_lshlrev_b32_e32 v80, 16, v81
	v_and_b32_e32 v81, 0xffff0000, v81
	v_and_b32_e32 v83, 0xffff0000, v78
	v_lshlrev_b32_e32 v78, 16, v79
	v_and_b32_e32 v79, 0xffff0000, v79
	s_waitcnt vmcnt(0)
	v_pk_mul_f32 v[86:87], v[74:75], v[80:81]
	v_pk_mul_f32 v[88:89], v[72:73], v[84:85]
	v_pk_fma_f32 v[86:87], v[70:71], v[78:79], v[86:87] neg_lo:[0,0,1] neg_hi:[0,0,1]
	v_pk_fma_f32 v[88:89], v[68:69], v[82:83], v[88:89] neg_lo:[0,0,1] neg_hi:[0,0,1]
	v_pk_mul_f32 v[70:71], v[70:71], v[80:81]
	v_pk_mul_f32 v[68:69], v[68:69], v[84:85]
	v_pk_fma_f32 v[70:71], v[74:75], v[78:79], v[70:71]
	v_pk_fma_f32 v[68:69], v[72:73], v[82:83], v[68:69]
	v_mov_b64_e32 v[74:75], s[12:13]
	v_cvt_pk_bf16_f32 v68, v68, v69
	v_cvt_pk_bf16_f32 v69, v70, v71
	v_lshl_add_u64 v[70:71], s[6:7], 0, v[76:77]
	v_mad_u64_u32 v[74:75], s[6:7], v70, s57, v[74:75]
	v_mad_i32_i24 v75, v71, s57, v75
	v_lshl_add_u64 v[66:67], v[74:75], 0, v[66:67]
	s_mov_b32 s6, 0xc0000
	v_add_co_u32_e32 v70, vcc, s6, v66
	v_cvt_pk_bf16_f32 v72, v88, v89
	v_cvt_pk_bf16_f32 v73, v86, v87
	s_mov_b32 s6, 0x180000
	s_nop 0
	v_addc_co_u32_e32 v71, vcc, 0, v67, vcc
	s_nop 1
	v_mov_b32_e32 v244, v72
	v_mov_b32_e32 v245, v73
	v_mov_b32_e32 v246, v68
	v_mov_b32_e32 v247, v69
	v_bfe_u32 v248, v193, 4, 1
	v_mul_u32_u24_e32 v248, 24, v248
	v_add_co_u32_e64 v248, s[98:99], v248, v66
	s_nop 1
	v_addc_co_u32_e64 v249, s[98:99], 0, v67, s[98:99]
	v_permlane16_swap_b32_e32 v244, v246
	v_permlane16_swap_b32_e32 v245, v247
	global_store_dwordx4 v[248:249], v[244:247], off offset:128
	s_nop 1
	v_mov_b32_e32 v244, v72
	v_mov_b32_e32 v245, v73
	v_mov_b32_e32 v246, v68
	v_mov_b32_e32 v247, v69
	v_bfe_u32 v248, v193, 4, 1
	v_mul_u32_u24_e32 v248, 24, v248
	v_add_co_u32_e64 v248, s[98:99], v248, v70
	s_nop 1
	v_addc_co_u32_e64 v249, s[98:99], 0, v71, s[98:99]
	v_permlane16_swap_b32_e32 v244, v246
	v_permlane16_swap_b32_e32 v245, v247
	global_store_dwordx4 v[248:249], v[244:247], off offset:128
	v_add_co_u32_e32 v70, vcc, s6, v66
	s_mov_b32 s6, 0x240000
	s_nop 0
	v_addc_co_u32_e32 v71, vcc, 0, v67, vcc
	v_add_co_u32_e32 v66, vcc, s6, v66
	s_nop 1
	v_mov_b32_e32 v244, v72
	v_mov_b32_e32 v245, v73
	v_mov_b32_e32 v246, v68
	v_mov_b32_e32 v247, v69
	v_bfe_u32 v248, v193, 4, 1
	v_mul_u32_u24_e32 v248, 24, v248
	v_add_co_u32_e64 v248, s[98:99], v248, v70
	s_nop 1
	v_addc_co_u32_e64 v249, s[98:99], 0, v71, s[98:99]
	v_permlane16_swap_b32_e32 v244, v246
	v_permlane16_swap_b32_e32 v245, v247
	global_store_dwordx4 v[248:249], v[244:247], off offset:128
	v_addc_co_u32_e32 v67, vcc, 0, v67, vcc
	s_nop 1
	v_mov_b32_e32 v244, v72
	v_mov_b32_e32 v245, v73
	v_mov_b32_e32 v246, v68
	v_mov_b32_e32 v247, v69
	v_bfe_u32 v248, v193, 4, 1
	v_mul_u32_u24_e32 v248, 24, v248
	v_add_co_u32_e64 v248, s[98:99], v248, v66
	s_nop 1
	v_addc_co_u32_e64 v249, s[98:99], 0, v67, s[98:99]
	v_permlane16_swap_b32_e32 v244, v246
	v_permlane16_swap_b32_e32 v245, v247
	global_store_dwordx4 v[248:249], v[244:247], off offset:128
	s_barrier
; #define LAS __attribute__((address_space(3)))
; __device__ __forceinline__ unsigned pk2(float lo, float hi) { unsigned r; asm("v_cvt_pk_bf16_f32 %0, %1, %2" : "=v"(r) : "v"(lo), "v"(hi)); return r; }
; __device__ __forceinline__ float rsq(float x) { return __builtin_amdgcn_rsqf(x); }
; template <int NNT>
; __device__ __forceinline__ void norm_store(const f32x4 (&acc)[8][NNT], const LAS float* part, bf16_t* dst, int fr) {
; #pragma unroll
;     for (int mt = 0; mt < 8; ++mt) {
;         const LAS f32x4* pp = (const LAS f32x4*)(part + (16 * mt + fr) * 8); const f32x4 a = pp[0], b = pp[1];
;         const float rs = rsq((((a[0] + a[1]) + (a[2] + a[3])) + ((b[0] + b[1]) + (b[2] + b[3]))) * (1.0f / 256.0f) + EPS);
; #pragma unroll
;         for (int nt = 0; nt < NNT; ++nt) { u32x2 o; o.x = pk2(acc[mt][nt][0] * rs, acc[mt][nt][1] * rs); o.y = pk2(acc[mt][nt][2] * rs, acc[mt][nt][3] * rs);
;             *(u32x2*)(dst + (size_t)(16 * mt) * DM + 16 * nt) = o; }
;     }
; }
	ds_read_b128 v[68:71], v215
	ds_read_b128 v[72:75], v215 offset:16
	v_lshl_add_u64 v[66:67], s[42:43], 1, v[170:171]
	s_mov_b32 s6, 0x8000
	s_cselect_b64 s[42:43], -1, 0
	s_waitcnt lgkmcnt(1)
	v_mov_b32_e32 v76, v68
	s_waitcnt lgkmcnt(0)
	v_mov_b32_e32 v77, v72
	v_mov_b32_e32 v72, v69
	v_pk_add_f32 v[68:69], v[76:77], v[72:73]
	v_mov_b32_e32 v72, v70
	v_mov_b32_e32 v73, v74
	v_mov_b32_e32 v74, v71
	v_pk_add_f32 v[70:71], v[72:73], v[74:75]
	s_cmp_lg_u32 s46, 0
	v_pk_add_f32 v[68:69], v[68:69], v[70:71]
	s_cselect_b64 s[90:91], -1, 0
	v_add_f32_e32 v68, v68, v69
	v_fmamk_f32 v68, v68, 0x3b800000, v189
	v_rsq_f32_e32 v68, v68
	s_nop 0
	v_mul_f32_e32 v62, v62, v68
	v_mul_f32_e32 v63, v63, v68
	v_mul_f32_e32 v58, v58, v68
	v_mul_f32_e32 v59, v59, v68
	v_cvt_pk_bf16_f32 v62, v62, v63
	v_mul_f32_e32 v63, v64, v68
	v_cvt_pk_bf16_f32 v58, v58, v59
	v_mul_f32_e32 v59, v60, v68
	v_mul_f32_e32 v64, v65, v68
	v_cvt_pk_bf16_f32 v63, v63, v64
	s_nop 1
	v_mov_b32_e32 v244, v62
	v_mov_b32_e32 v245, v63
	v_mul_f32_e32 v60, v61, v68
	v_cvt_pk_bf16_f32 v59, v59, v60
	v_mov_b32_e32 v246, v58
	v_mov_b32_e32 v247, v59
	v_bfe_u32 v248, v193, 4, 1
	v_mul_u32_u24_e32 v248, 24, v248
	v_add_co_u32_e64 v248, s[98:99], v248, v66
	s_nop 1
	v_addc_co_u32_e64 v249, s[98:99], 0, v67, s[98:99]
	v_permlane16_swap_b32_e32 v244, v246
	v_permlane16_swap_b32_e32 v245, v247
	global_store_dwordx4 v[248:249], v[244:247], off
	ds_read_b128 v[58:61], v215 offset:512
	ds_read_b128 v[62:65], v215 offset:528
	s_waitcnt lgkmcnt(1)
	v_mov_b32_e32 v68, v58
	s_waitcnt lgkmcnt(0)
	v_mov_b32_e32 v69, v62
	v_mov_b32_e32 v62, v59
	v_pk_add_f32 v[58:59], v[68:69], v[62:63]
	v_mov_b32_e32 v62, v60
	v_mov_b32_e32 v63, v64
	v_mov_b32_e32 v64, v61
	v_pk_add_f32 v[60:61], v[62:63], v[64:65]
	s_nop 0
	v_pk_add_f32 v[58:59], v[58:59], v[60:61]
	s_nop 0
	v_add_f32_e32 v58, v58, v59
	v_fmamk_f32 v58, v58, 0x3b800000, v189
	v_rsq_f32_e32 v58, v58
	s_nop 0
	v_mul_f32_e32 v54, v54, v58
	v_mul_f32_e32 v55, v55, v58
	v_cvt_pk_bf16_f32 v54, v54, v55
	v_mul_f32_e32 v55, v56, v58
	v_mul_f32_e32 v56, v57, v58
	v_cvt_pk_bf16_f32 v55, v55, v56
	v_add_co_u32_e32 v56, vcc, s6, v66
	v_mul_f32_e32 v50, v50, v58
	v_mul_f32_e32 v51, v51, v58
	v_addc_co_u32_e32 v57, vcc, 0, v67, vcc
	v_cvt_pk_bf16_f32 v50, v50, v51
	v_mul_f32_e32 v51, v52, v58
	s_nop 1
	v_mov_b32_e32 v244, v54
	v_mov_b32_e32 v245, v55
	v_mul_f32_e32 v52, v53, v58
	v_cvt_pk_bf16_f32 v51, v51, v52
	v_mov_b32_e32 v246, v50
	v_mov_b32_e32 v247, v51
	v_bfe_u32 v248, v193, 4, 1
	v_mul_u32_u24_e32 v248, 24, v248
	v_add_co_u32_e64 v248, s[98:99], v248, v56
	s_nop 1
	v_addc_co_u32_e64 v249, s[98:99], 0, v57, s[98:99]
	v_permlane16_swap_b32_e32 v244, v246
	v_permlane16_swap_b32_e32 v245, v247
	global_store_dwordx4 v[248:249], v[244:247], off
	ds_read_b128 v[50:53], v215 offset:1024
	ds_read_b128 v[54:57], v215 offset:1040
	s_mov_b32 s6, 0x18000
	s_waitcnt lgkmcnt(1)
	v_mov_b32_e32 v58, v50
	s_waitcnt lgkmcnt(0)
	v_mov_b32_e32 v59, v54
	v_mov_b32_e32 v54, v51
	v_pk_add_f32 v[50:51], v[58:59], v[54:55]
	v_mov_b32_e32 v54, v52
	v_mov_b32_e32 v55, v56
	v_mov_b32_e32 v56, v53
	v_pk_add_f32 v[52:53], v[54:55], v[56:57]
	s_nop 0
	v_pk_add_f32 v[50:51], v[50:51], v[52:53]
	s_nop 0
	v_add_f32_e32 v50, v50, v51
	v_fmamk_f32 v50, v50, 0x3b800000, v189
	v_rsq_f32_e32 v50, v50
	s_nop 0
	v_mul_f32_e32 v46, v46, v50
	v_mul_f32_e32 v47, v47, v50
	v_cvt_pk_bf16_f32 v46, v46, v47
	v_mul_f32_e32 v47, v48, v50
	v_mul_f32_e32 v48, v49, v50
	v_cvt_pk_bf16_f32 v47, v47, v48
	v_add_co_u32_e32 v48, vcc, s72, v66
	v_mul_f32_e32 v42, v42, v50
	v_mul_f32_e32 v43, v43, v50
	v_addc_co_u32_e32 v49, vcc, 0, v67, vcc
	v_cvt_pk_bf16_f32 v42, v42, v43
	v_mul_f32_e32 v43, v44, v50
	s_nop 1
	v_mov_b32_e32 v244, v46
	v_mov_b32_e32 v245, v47
	v_mul_f32_e32 v44, v45, v50
	v_cvt_pk_bf16_f32 v43, v43, v44
	v_mov_b32_e32 v246, v42
	v_mov_b32_e32 v247, v43
	v_bfe_u32 v248, v193, 4, 1
	v_mul_u32_u24_e32 v248, 24, v248
	v_add_co_u32_e64 v248, s[98:99], v248, v48
	s_nop 1
	v_addc_co_u32_e64 v249, s[98:99], 0, v49, s[98:99]
	v_permlane16_swap_b32_e32 v244, v246
	v_permlane16_swap_b32_e32 v245, v247
	global_store_dwordx4 v[248:249], v[244:247], off
	ds_read_b128 v[42:45], v215 offset:1536
	ds_read_b128 v[46:49], v215 offset:1552
	s_waitcnt lgkmcnt(1)
	v_mov_b32_e32 v50, v42
	s_waitcnt lgkmcnt(0)
	v_mov_b32_e32 v51, v46
	v_mov_b32_e32 v46, v43
	v_pk_add_f32 v[42:43], v[50:51], v[46:47]
	v_mov_b32_e32 v46, v44
	v_mov_b32_e32 v47, v48
	v_mov_b32_e32 v48, v45
	v_pk_add_f32 v[44:45], v[46:47], v[48:49]
	s_nop 0
	v_pk_add_f32 v[42:43], v[42:43], v[44:45]
	s_nop 0
	v_add_f32_e32 v42, v42, v43
	v_fmamk_f32 v42, v42, 0x3b800000, v189
	v_rsq_f32_e32 v42, v42
	s_nop 0
	v_mul_f32_e32 v38, v38, v42
	v_mul_f32_e32 v39, v39, v42
	v_cvt_pk_bf16_f32 v38, v38, v39
	v_mul_f32_e32 v39, v40, v42
	v_mul_f32_e32 v40, v41, v42
	v_cvt_pk_bf16_f32 v39, v39, v40
	v_add_co_u32_e32 v40, vcc, s6, v66
	v_mul_f32_e32 v34, v34, v42
	v_mul_f32_e32 v35, v35, v42
	v_addc_co_u32_e32 v41, vcc, 0, v67, vcc
	v_cvt_pk_bf16_f32 v34, v34, v35
	v_mul_f32_e32 v35, v36, v42
	s_nop 1
	v_mov_b32_e32 v244, v38
	v_mov_b32_e32 v245, v39
	v_mul_f32_e32 v36, v37, v42
	v_cvt_pk_bf16_f32 v35, v35, v36
	v_mov_b32_e32 v246, v34
	v_mov_b32_e32 v247, v35
	v_bfe_u32 v248, v193, 4, 1
	v_mul_u32_u24_e32 v248, 24, v248
	v_add_co_u32_e64 v248, s[98:99], v248, v40
	s_nop 1
	v_addc_co_u32_e64 v249, s[98:99], 0, v41, s[98:99]
	v_permlane16_swap_b32_e32 v244, v246
	v_permlane16_swap_b32_e32 v245, v247
	global_store_dwordx4 v[248:249], v[244:247], off
	ds_read_b128 v[34:37], v215 offset:2048
	ds_read_b128 v[38:41], v215 offset:2064
	s_mov_b32 s6, 0x20000
	s_waitcnt lgkmcnt(1)
; #define LAS __attribute__((address_space(3)))
; __device__ __forceinline__ unsigned pk2(float lo, float hi) { unsigned r; asm("v_cvt_pk_bf16_f32 %0, %1, %2" : "=v"(r) : "v"(lo), "v"(hi)); return r; }
; __device__ __forceinline__ float rsq(float x) { return __builtin_amdgcn_rsqf(x); }
; template <int NKS, int NNT>
; __device__ __forceinline__ void wgemm(f32x4 (&acc)[8][NNT], const LAS bf16_t* A, const int lda, const bf16_t* Bp, const int ldb) {
;     u32x4 bf[NNT][NKS];
; #pragma unroll
;     for (int nt = 0; nt < NNT; ++nt) ldfr(bf[nt], Bp + (size_t)(16 * nt) * ldb);
; #pragma unroll
;     for (int nt = 0; nt < NNT; ++nt) pin(bf[nt]);
; #pragma unroll
;     for (int mt = 0; mt < 8; ++mt) {
;         bf16x8 af[NKS];
; #pragma unroll
;         for (int ks = 0; ks < NKS; ++ks) af[ks] = *(const LAS bf16x8*)(A + (16 * mt) * lda + 32 * ks);
; template <int NNT>
; __device__ __forceinline__ void norm_store(const f32x4 (&acc)[8][NNT], const LAS float* part, bf16_t* dst, int fr) {
; #pragma unroll
;     for (int mt = 0; mt < 8; ++mt) {
;         const LAS f32x4* pp = (const LAS f32x4*)(part + (16 * mt + fr) * 8); const f32x4 a = pp[0], b = pp[1];
;         const float rs = rsq((((a[0] + a[1]) + (a[2] + a[3])) + ((b[0] + b[1]) + (b[2] + b[3]))) * (1.0f / 256.0f) + EPS);
; #pragma unroll
;         for (int nt = 0; nt < NNT; ++nt) { u32x2 o; o.x = pk2(acc[mt][nt][0] * rs, acc[mt][nt][1] * rs); o.y = pk2(acc[mt][nt][2] * rs, acc[mt][nt][3] * rs);
;             *(u32x2*)(dst + (size_t)(16 * mt) * DM + 16 * nt) = o; }
;     }
; }
	v_mov_b32_e32 v42, v34
	s_waitcnt lgkmcnt(0)
	v_mov_b32_e32 v43, v38
	v_mov_b32_e32 v38, v35
	v_pk_add_f32 v[34:35], v[42:43], v[38:39]
	v_mov_b32_e32 v38, v36
	v_mov_b32_e32 v39, v40
	v_mov_b32_e32 v40, v37
	v_pk_add_f32 v[36:37], v[38:39], v[40:41]
	s_nop 0
	v_pk_add_f32 v[34:35], v[34:35], v[36:37]
	s_nop 0
	v_add_f32_e32 v34, v34, v35
	v_fmamk_f32 v34, v34, 0x3b800000, v189
	v_rsq_f32_e32 v34, v34
	s_nop 0
	v_mul_f32_e32 v30, v30, v34
	v_mul_f32_e32 v31, v31, v34
	v_cvt_pk_bf16_f32 v30, v30, v31
	v_mul_f32_e32 v31, v32, v34
	v_mul_f32_e32 v32, v33, v34
	v_cvt_pk_bf16_f32 v31, v31, v32
	v_add_co_u32_e32 v32, vcc, s6, v66
	v_mul_f32_e32 v26, v26, v34
	v_mul_f32_e32 v27, v27, v34
	v_addc_co_u32_e32 v33, vcc, 0, v67, vcc
	v_cvt_pk_bf16_f32 v26, v26, v27
	v_mul_f32_e32 v27, v28, v34
	s_nop 1
	v_mov_b32_e32 v244, v30
	v_mov_b32_e32 v245, v31
	v_mul_f32_e32 v28, v29, v34
	v_cvt_pk_bf16_f32 v27, v27, v28
	v_mov_b32_e32 v246, v26
	v_mov_b32_e32 v247, v27
	v_bfe_u32 v248, v193, 4, 1
	v_mul_u32_u24_e32 v248, 24, v248
	v_add_co_u32_e64 v248, s[98:99], v248, v32
	s_nop 1
	v_addc_co_u32_e64 v249, s[98:99], 0, v33, s[98:99]
	v_permlane16_swap_b32_e32 v244, v246
	v_permlane16_swap_b32_e32 v245, v247
	global_store_dwordx4 v[248:249], v[244:247], off
	ds_read_b128 v[26:29], v215 offset:2560
	ds_read_b128 v[30:33], v215 offset:2576
	s_mov_b32 s6, 0x28000
	s_waitcnt lgkmcnt(1)
	v_mov_b32_e32 v34, v26
	s_waitcnt lgkmcnt(0)
	v_mov_b32_e32 v35, v30
	v_mov_b32_e32 v30, v27
	v_pk_add_f32 v[26:27], v[34:35], v[30:31]
	v_mov_b32_e32 v30, v28
	v_mov_b32_e32 v31, v32
	v_mov_b32_e32 v32, v29
	v_pk_add_f32 v[28:29], v[30:31], v[32:33]
	s_nop 0
	v_pk_add_f32 v[26:27], v[26:27], v[28:29]
	s_nop 0
	v_add_f32_e32 v26, v26, v27
	v_fmamk_f32 v26, v26, 0x3b800000, v189
	v_rsq_f32_e32 v26, v26
	s_nop 0
	v_mul_f32_e32 v22, v22, v26
	v_mul_f32_e32 v23, v23, v26
	v_cvt_pk_bf16_f32 v22, v22, v23
	v_mul_f32_e32 v23, v24, v26
	v_mul_f32_e32 v24, v25, v26
	v_cvt_pk_bf16_f32 v23, v23, v24
	v_add_co_u32_e32 v24, vcc, s6, v66
	v_mul_f32_e32 v18, v18, v26
	v_mul_f32_e32 v19, v19, v26
	v_addc_co_u32_e32 v25, vcc, 0, v67, vcc
	v_cvt_pk_bf16_f32 v18, v18, v19
	v_mul_f32_e32 v19, v20, v26
	s_nop 1
	v_mov_b32_e32 v244, v22
	v_mov_b32_e32 v245, v23
	v_mul_f32_e32 v20, v21, v26
	v_cvt_pk_bf16_f32 v19, v19, v20
	v_mov_b32_e32 v246, v18
	v_mov_b32_e32 v247, v19
	v_bfe_u32 v248, v193, 4, 1
	v_mul_u32_u24_e32 v248, 24, v248
	v_add_co_u32_e64 v248, s[98:99], v248, v24
	s_nop 1
	v_addc_co_u32_e64 v249, s[98:99], 0, v25, s[98:99]
	v_permlane16_swap_b32_e32 v244, v246
	v_permlane16_swap_b32_e32 v245, v247
	global_store_dwordx4 v[248:249], v[244:247], off
	ds_read_b128 v[18:21], v215 offset:3072
	ds_read_b128 v[22:25], v215 offset:3088
	s_mov_b32 s6, 0x30000
	s_waitcnt lgkmcnt(1)
	v_mov_b32_e32 v26, v18
	s_waitcnt lgkmcnt(0)
	v_mov_b32_e32 v27, v22
	v_mov_b32_e32 v22, v19
	v_pk_add_f32 v[18:19], v[26:27], v[22:23]
	v_mov_b32_e32 v22, v20
	v_mov_b32_e32 v23, v24
	v_mov_b32_e32 v24, v21
	v_pk_add_f32 v[20:21], v[22:23], v[24:25]
	s_nop 0
	v_pk_add_f32 v[18:19], v[18:19], v[20:21]
	s_nop 0
	v_add_f32_e32 v18, v18, v19
	v_fmamk_f32 v18, v18, 0x3b800000, v189
	v_rsq_f32_e32 v18, v18
	s_nop 0
	v_mul_f32_e32 v14, v14, v18
	v_mul_f32_e32 v15, v15, v18
	v_cvt_pk_bf16_f32 v14, v14, v15
	v_mul_f32_e32 v15, v16, v18
	v_mul_f32_e32 v16, v17, v18
	v_cvt_pk_bf16_f32 v15, v15, v16
	v_add_co_u32_e32 v16, vcc, s6, v66
	v_mul_f32_e32 v10, v10, v18
	v_mul_f32_e32 v11, v11, v18
	v_addc_co_u32_e32 v17, vcc, 0, v67, vcc
	v_cvt_pk_bf16_f32 v10, v10, v11
	v_mul_f32_e32 v11, v12, v18
	s_nop 1
	v_mov_b32_e32 v244, v14
	v_mov_b32_e32 v245, v15
	v_mul_f32_e32 v12, v13, v18
	v_cvt_pk_bf16_f32 v11, v11, v12
	v_mov_b32_e32 v246, v10
	v_mov_b32_e32 v247, v11
	v_bfe_u32 v248, v193, 4, 1
	v_mul_u32_u24_e32 v248, 24, v248
	v_add_co_u32_e64 v248, s[98:99], v248, v16
	s_nop 1
	v_addc_co_u32_e64 v249, s[98:99], 0, v17, s[98:99]
	v_permlane16_swap_b32_e32 v244, v246
	v_permlane16_swap_b32_e32 v245, v247
	global_store_dwordx4 v[248:249], v[244:247], off
	ds_read_b128 v[10:13], v215 offset:3584
	ds_read_b128 v[14:17], v215 offset:3600
	s_mov_b32 s6, 0x38000
	s_waitcnt lgkmcnt(1)
	v_mov_b32_e32 v18, v10
	s_waitcnt lgkmcnt(0)
	v_mov_b32_e32 v19, v14
	v_mov_b32_e32 v14, v11
	v_pk_add_f32 v[10:11], v[18:19], v[14:15]
	v_mov_b32_e32 v14, v12
	v_mov_b32_e32 v15, v16
	v_mov_b32_e32 v16, v13
	v_pk_add_f32 v[12:13], v[14:15], v[16:17]
	s_nop 0
	v_pk_add_f32 v[10:11], v[10:11], v[12:13]
	s_nop 0
	v_add_f32_e32 v10, v10, v11
	v_fmamk_f32 v10, v10, 0x3b800000, v189
	v_rsq_f32_e32 v10, v10
	s_nop 0
	v_mul_f32_e32 v2, v2, v10
	v_mul_f32_e32 v3, v3, v10
	v_cvt_pk_bf16_f32 v2, v2, v3
	v_mul_f32_e32 v3, v4, v10
	v_mul_f32_e32 v4, v5, v10
	v_cvt_pk_bf16_f32 v3, v3, v4
	v_add_co_u32_e32 v4, vcc, s6, v66
	s_mul_i32 s6, s55, 48
	s_nop 0
	v_addc_co_u32_e32 v5, vcc, 0, v67, vcc
	s_nop 1
	v_mov_b32_e32 v244, v2
	v_mov_b32_e32 v245, v3
	v_mul_f32_e32 v2, v6, v10
	v_mul_f32_e32 v3, v7, v10
	v_cvt_pk_bf16_f32 v2, v2, v3
	v_mul_f32_e32 v3, v8, v10
	v_mul_f32_e32 v6, v9, v10
	v_cvt_pk_bf16_f32 v3, v3, v6
	v_mov_b32_e32 v246, v2
	v_mov_b32_e32 v247, v3
	v_bfe_u32 v248, v193, 4, 1
	v_mul_u32_u24_e32 v248, 24, v248
	v_add_co_u32_e64 v248, s[98:99], v248, v4
	s_nop 1
	v_addc_co_u32_e64 v249, s[98:99], 0, v5, s[98:99]
	v_permlane16_swap_b32_e32 v244, v246
	v_permlane16_swap_b32_e32 v245, v247
	global_store_dwordx4 v[248:249], v[244:247], off
	v_mul_u32_u24_e32 v2, 0x190, v217
	v_add3_u32 v162, 0, v2, v0
	v_or_b32_e32 v4, s6, v217
	v_mov_b64_e32 v[2:3], s[10:11]
	s_movk_i32 s6, 0x180
	v_mad_i64_i32 v[2:3], s[6:7], v4, s6, v[2:3]
	v_lshl_add_u64 v[10:11], v[2:3], 0, v[0:1]
	s_movk_i32 s6, 0x1000
	v_add_co_u32_e32 v12, vcc, s6, v10
	global_load_dwordx4 v[154:157], v[10:11], off
	global_load_dwordx4 v[150:153], v[10:11], off offset:64
	global_load_dwordx4 v[142:145], v[10:11], off offset:128
	global_load_dwordx4 v[138:141], v[10:11], off offset:192
	global_load_dwordx4 v[6:9], v[10:11], off offset:256
	global_load_dwordx4 v[2:5], v[10:11], off offset:320
	v_addc_co_u32_e32 v13, vcc, 0, v11, vcc
	v_add_co_u32_e32 v10, vcc, s68, v10
	global_load_dwordx4 v[22:25], v[12:13], off offset:2048
	global_load_dwordx4 v[98:101], v[12:13], off offset:2112
	global_load_dwordx4 v[102:105], v[12:13], off offset:2176
	global_load_dwordx4 v[106:109], v[12:13], off offset:2240
	global_load_dwordx4 v[110:113], v[12:13], off offset:2304
	global_load_dwordx4 v[114:117], v[12:13], off offset:2368
	v_addc_co_u32_e32 v11, vcc, 0, v11, vcc
	global_load_dwordx4 v[146:149], v[10:11], off
	global_load_dwordx4 v[118:121], v[10:11], off offset:64
	global_load_dwordx4 v[122:125], v[10:11], off offset:128
	global_load_dwordx4 v[126:129], v[10:11], off offset:192
	global_load_dwordx4 v[130:133], v[10:11], off offset:256
	global_load_dwordx4 v[134:137], v[10:11], off offset:320
	s_waitcnt vmcnt(12)
; #define LAS __attribute__((address_space(3)))
; __device__ __forceinline__ f32x4 mfma16(bf16x8 a, bf16x8 b, f32x4 c) { return __builtin_amdgcn_mfma_f32_16x16x32_bf16(a, b, c, 0, 0, 0); }
; template <int NKS, int NNT>
; __device__ __forceinline__ void wgemm(f32x4 (&acc)[8][NNT], const LAS bf16_t* A, const int lda, const bf16_t* Bp, const int ldb) {
;     u32x4 bf[NNT][NKS];
; #pragma unroll
;     for (int nt = 0; nt < NNT; ++nt) ldfr(bf[nt], Bp + (size_t)(16 * nt) * ldb);
; #pragma unroll
;     for (int nt = 0; nt < NNT; ++nt) pin(bf[nt]);
; #pragma unroll
;     for (int mt = 0; mt < 8; ++mt) {
;         bf16x8 af[NKS];
; #pragma unroll
;         for (int ks = 0; ks < NKS; ++ks) af[ks] = *(const LAS bf16x8*)(A + (16 * mt) * lda + 32 * ks);
; #pragma unroll
;         for (int nt = 0; nt < NNT; ++nt) { f32x4 a = (f32x4){0.f, 0.f, 0.f, 0.f};
; #pragma unroll
;             for (int ks = 0; ks < NKS; ++ks) a = mfma16(as_bf16x8(bf[nt][ks]), af[ks], a);
;             acc[mt][nt] = a; }
;     }
; }
	s_waitcnt vmcnt(6)
	s_waitcnt vmcnt(0)
	ds_read_b128 v[10:13], v162
	ds_read_b128 v[14:17], v162 offset:64
	ds_read_b128 v[18:21], v162 offset:128
	ds_read_b128 v[26:29], v162 offset:192
	ds_read_b128 v[30:33], v162 offset:256
	ds_read_b128 v[34:37], v162 offset:320
	s_waitcnt lgkmcnt(5)
	v_mfma_f32_16x16x32_bf16 v[38:41], v[154:157], v[10:13], 0
	s_and_b64 vcc, exec, s[42:43]
	s_waitcnt lgkmcnt(4)
	v_mfma_f32_16x16x32_bf16 v[38:41], v[150:153], v[14:17], v[38:41]
	s_waitcnt lgkmcnt(3)
	v_mfma_f32_16x16x32_bf16 v[38:41], v[142:145], v[18:21], v[38:41]
	s_waitcnt lgkmcnt(2)
	v_mfma_f32_16x16x32_bf16 v[38:41], v[138:141], v[26:29], v[38:41]
	s_waitcnt lgkmcnt(1)
	v_mfma_f32_16x16x32_bf16 v[38:41], v[6:9], v[30:33], v[38:41]
	s_waitcnt lgkmcnt(0)
	v_mfma_f32_16x16x32_bf16 v[82:85], v[2:5], v[34:37], v[38:41]
	v_mfma_f32_16x16x32_bf16 v[38:41], v[22:25], v[10:13], 0
	v_mfma_f32_16x16x32_bf16 v[10:13], v[146:149], v[10:13], 0
	v_mfma_f32_16x16x32_bf16 v[38:41], v[98:101], v[14:17], v[38:41]
	v_mfma_f32_16x16x32_bf16 v[10:13], v[118:121], v[14:17], v[10:13]
	v_mfma_f32_16x16x32_bf16 v[38:41], v[102:105], v[18:21], v[38:41]
	v_mfma_f32_16x16x32_bf16 v[10:13], v[122:125], v[18:21], v[10:13]
	v_mfma_f32_16x16x32_bf16 v[38:41], v[106:109], v[26:29], v[38:41]
	v_mfma_f32_16x16x32_bf16 v[10:13], v[126:129], v[26:29], v[10:13]
	v_mfma_f32_16x16x32_bf16 v[38:41], v[110:113], v[30:33], v[38:41]
	v_mfma_f32_16x16x32_bf16 v[10:13], v[130:133], v[30:33], v[10:13]
	v_mfma_f32_16x16x32_bf16 v[90:93], v[114:117], v[34:37], v[38:41]
	v_mfma_f32_16x16x32_bf16 v[94:97], v[134:137], v[34:37], v[10:13]
	s_nop 5
	ds_read_b128 v[10:13], v162 offset:6400
	ds_read_b128 v[14:17], v162 offset:6464
	ds_read_b128 v[18:21], v162 offset:6528
	ds_read_b128 v[26:29], v162 offset:6592
	ds_read_b128 v[30:33], v162 offset:6656
	ds_read_b128 v[34:37], v162 offset:6720
	s_waitcnt lgkmcnt(5)
	v_mfma_f32_16x16x32_bf16 v[38:41], v[154:157], v[10:13], 0
	s_waitcnt lgkmcnt(4)
	v_mfma_f32_16x16x32_bf16 v[38:41], v[150:153], v[14:17], v[38:41]
	s_waitcnt lgkmcnt(3)
	v_mfma_f32_16x16x32_bf16 v[38:41], v[142:145], v[18:21], v[38:41]
	s_waitcnt lgkmcnt(2)
	v_mfma_f32_16x16x32_bf16 v[38:41], v[138:141], v[26:29], v[38:41]
	s_waitcnt lgkmcnt(1)
	v_mfma_f32_16x16x32_bf16 v[38:41], v[6:9], v[30:33], v[38:41]
	s_waitcnt lgkmcnt(0)
	v_mfma_f32_16x16x32_bf16 v[74:77], v[2:5], v[34:37], v[38:41]
	v_mfma_f32_16x16x32_bf16 v[38:41], v[22:25], v[10:13], 0
	v_mfma_f32_16x16x32_bf16 v[10:13], v[146:149], v[10:13], 0
	v_mfma_f32_16x16x32_bf16 v[38:41], v[98:101], v[14:17], v[38:41]
	v_mfma_f32_16x16x32_bf16 v[10:13], v[118:121], v[14:17], v[10:13]
	v_mfma_f32_16x16x32_bf16 v[38:41], v[102:105], v[18:21], v[38:41]
	v_mfma_f32_16x16x32_bf16 v[10:13], v[122:125], v[18:21], v[10:13]
	v_mfma_f32_16x16x32_bf16 v[38:41], v[106:109], v[26:29], v[38:41]
	v_mfma_f32_16x16x32_bf16 v[10:13], v[126:129], v[26:29], v[10:13]
	v_mfma_f32_16x16x32_bf16 v[38:41], v[110:113], v[30:33], v[38:41]
	v_mfma_f32_16x16x32_bf16 v[10:13], v[130:133], v[30:33], v[10:13]
	v_mfma_f32_16x16x32_bf16 v[78:81], v[114:117], v[34:37], v[38:41]
	v_mfma_f32_16x16x32_bf16 v[86:89], v[134:137], v[34:37], v[10:13]
	s_nop 5
	ds_read_b128 v[10:13], v162 offset:12800
	ds_read_b128 v[14:17], v162 offset:12864
	ds_read_b128 v[18:21], v162 offset:12928
	ds_read_b128 v[26:29], v162 offset:12992
	ds_read_b128 v[30:33], v162 offset:13056
	ds_read_b128 v[34:37], v162 offset:13120
	s_waitcnt lgkmcnt(5)
	v_mfma_f32_16x16x32_bf16 v[38:41], v[154:157], v[10:13], 0
	s_waitcnt lgkmcnt(4)
	v_mfma_f32_16x16x32_bf16 v[38:41], v[150:153], v[14:17], v[38:41]
	s_waitcnt lgkmcnt(3)
	v_mfma_f32_16x16x32_bf16 v[38:41], v[142:145], v[18:21], v[38:41]
	s_waitcnt lgkmcnt(2)
	v_mfma_f32_16x16x32_bf16 v[38:41], v[138:141], v[26:29], v[38:41]
	s_waitcnt lgkmcnt(1)
	v_mfma_f32_16x16x32_bf16 v[38:41], v[6:9], v[30:33], v[38:41]
	s_waitcnt lgkmcnt(0)
	v_mfma_f32_16x16x32_bf16 v[62:65], v[2:5], v[34:37], v[38:41]
	v_mfma_f32_16x16x32_bf16 v[38:41], v[22:25], v[10:13], 0
	v_mfma_f32_16x16x32_bf16 v[10:13], v[146:149], v[10:13], 0
	v_mfma_f32_16x16x32_bf16 v[38:41], v[98:101], v[14:17], v[38:41]
	v_mfma_f32_16x16x32_bf16 v[10:13], v[118:121], v[14:17], v[10:13]
	v_mfma_f32_16x16x32_bf16 v[38:41], v[102:105], v[18:21], v[38:41]
	v_mfma_f32_16x16x32_bf16 v[10:13], v[122:125], v[18:21], v[10:13]
	v_mfma_f32_16x16x32_bf16 v[38:41], v[106:109], v[26:29], v[38:41]
	v_mfma_f32_16x16x32_bf16 v[10:13], v[126:129], v[26:29], v[10:13]
	v_mfma_f32_16x16x32_bf16 v[38:41], v[110:113], v[30:33], v[38:41]
	v_mfma_f32_16x16x32_bf16 v[10:13], v[130:133], v[30:33], v[10:13]
	v_mfma_f32_16x16x32_bf16 v[66:69], v[114:117], v[34:37], v[38:41]
	v_mfma_f32_16x16x32_bf16 v[70:73], v[134:137], v[34:37], v[10:13]
	s_nop 5
	ds_read_b128 v[10:13], v162 offset:19200
	ds_read_b128 v[14:17], v162 offset:19264
	ds_read_b128 v[18:21], v162 offset:19328
	ds_read_b128 v[26:29], v162 offset:19392
	ds_read_b128 v[30:33], v162 offset:19456
	ds_read_b128 v[34:37], v162 offset:19520
	s_waitcnt lgkmcnt(5)
	v_mfma_f32_16x16x32_bf16 v[38:41], v[154:157], v[10:13], 0
	s_waitcnt lgkmcnt(4)
	v_mfma_f32_16x16x32_bf16 v[38:41], v[150:153], v[14:17], v[38:41]
	s_waitcnt lgkmcnt(3)
	v_mfma_f32_16x16x32_bf16 v[38:41], v[142:145], v[18:21], v[38:41]
	s_waitcnt lgkmcnt(2)
	v_mfma_f32_16x16x32_bf16 v[38:41], v[138:141], v[26:29], v[38:41]
	s_waitcnt lgkmcnt(1)
	v_mfma_f32_16x16x32_bf16 v[38:41], v[6:9], v[30:33], v[38:41]
	s_waitcnt lgkmcnt(0)
; #define LAS __attribute__((address_space(3)))
; __device__ __forceinline__ f32x4 mfma16(bf16x8 a, bf16x8 b, f32x4 c) { return __builtin_amdgcn_mfma_f32_16x16x32_bf16(a, b, c, 0, 0, 0); }
; template <int NKS, int NNT>
; __device__ __forceinline__ void wgemm(f32x4 (&acc)[8][NNT], const LAS bf16_t* A, const int lda, const bf16_t* Bp, const int ldb) {
;     u32x4 bf[NNT][NKS];
; #pragma unroll
;     for (int nt = 0; nt < NNT; ++nt) ldfr(bf[nt], Bp + (size_t)(16 * nt) * ldb);
; #pragma unroll
;     for (int nt = 0; nt < NNT; ++nt) pin(bf[nt]);
; #pragma unroll
;     for (int mt = 0; mt < 8; ++mt) {
;         bf16x8 af[NKS];
; #pragma unroll
;         for (int ks = 0; ks < NKS; ++ks) af[ks] = *(const LAS bf16x8*)(A + (16 * mt) * lda + 32 * ks);
; #pragma unroll
;         for (int nt = 0; nt < NNT; ++nt) { f32x4 a = (f32x4){0.f, 0.f, 0.f, 0.f};
; #pragma unroll
;             for (int ks = 0; ks < NKS; ++ks) a = mfma16(as_bf16x8(bf[nt][ks]), af[ks], a);
;             acc[mt][nt] = a; }
;     }
; }
	v_mfma_f32_16x16x32_bf16 v[50:53], v[2:5], v[34:37], v[38:41]
	v_mfma_f32_16x16x32_bf16 v[38:41], v[22:25], v[10:13], 0
	v_mfma_f32_16x16x32_bf16 v[10:13], v[146:149], v[10:13], 0
	v_mfma_f32_16x16x32_bf16 v[38:41], v[98:101], v[14:17], v[38:41]
	v_mfma_f32_16x16x32_bf16 v[10:13], v[118:121], v[14:17], v[10:13]
	v_mfma_f32_16x16x32_bf16 v[38:41], v[102:105], v[18:21], v[38:41]
	v_mfma_f32_16x16x32_bf16 v[10:13], v[122:125], v[18:21], v[10:13]
	v_mfma_f32_16x16x32_bf16 v[38:41], v[106:109], v[26:29], v[38:41]
	v_mfma_f32_16x16x32_bf16 v[10:13], v[126:129], v[26:29], v[10:13]
	v_mfma_f32_16x16x32_bf16 v[38:41], v[110:113], v[30:33], v[38:41]
	v_mfma_f32_16x16x32_bf16 v[10:13], v[130:133], v[30:33], v[10:13]
	v_mfma_f32_16x16x32_bf16 v[54:57], v[114:117], v[34:37], v[38:41]
	v_mfma_f32_16x16x32_bf16 v[58:61], v[134:137], v[34:37], v[10:13]
	s_nop 5
	ds_read_b128 v[10:13], v162 offset:25600
	ds_read_b128 v[14:17], v162 offset:25664
	ds_read_b128 v[18:21], v162 offset:25728
	ds_read_b128 v[26:29], v162 offset:25792
	ds_read_b128 v[34:37], v162 offset:25856
	ds_read_b128 v[42:45], v162 offset:25920
	s_waitcnt lgkmcnt(5)
	v_mfma_f32_16x16x32_bf16 v[30:33], v[154:157], v[10:13], 0
	v_mfma_f32_16x16x32_bf16 v[38:41], v[22:25], v[10:13], 0
	v_mfma_f32_16x16x32_bf16 v[10:13], v[146:149], v[10:13], 0
	s_waitcnt lgkmcnt(4)
	v_mfma_f32_16x16x32_bf16 v[30:33], v[150:153], v[14:17], v[30:33]
	v_mfma_f32_16x16x32_bf16 v[38:41], v[98:101], v[14:17], v[38:41]
	v_mfma_f32_16x16x32_bf16 v[10:13], v[118:121], v[14:17], v[10:13]
	s_waitcnt lgkmcnt(3)
	v_mfma_f32_16x16x32_bf16 v[30:33], v[142:145], v[18:21], v[30:33]
	v_mfma_f32_16x16x32_bf16 v[38:41], v[102:105], v[18:21], v[38:41]
	v_mfma_f32_16x16x32_bf16 v[10:13], v[122:125], v[18:21], v[10:13]
	s_waitcnt lgkmcnt(2)
	v_mfma_f32_16x16x32_bf16 v[30:33], v[138:141], v[26:29], v[30:33]
	v_mfma_f32_16x16x32_bf16 v[38:41], v[106:109], v[26:29], v[38:41]
	v_mfma_f32_16x16x32_bf16 v[10:13], v[126:129], v[26:29], v[10:13]
	s_waitcnt lgkmcnt(1)
	v_mfma_f32_16x16x32_bf16 v[30:33], v[6:9], v[34:37], v[30:33]
	v_mfma_f32_16x16x32_bf16 v[38:41], v[110:113], v[34:37], v[38:41]
	v_mfma_f32_16x16x32_bf16 v[10:13], v[130:133], v[34:37], v[10:13]
	s_waitcnt lgkmcnt(0)
	v_mfma_f32_16x16x32_bf16 v[30:33], v[2:5], v[42:45], v[30:33]
	v_mfma_f32_16x16x32_bf16 v[38:41], v[114:117], v[42:45], v[38:41]
	v_mfma_f32_16x16x32_bf16 v[46:49], v[134:137], v[42:45], v[10:13]
	s_nop 3
	ds_read_b128 v[10:13], v162 offset:32000
	ds_read_b128 v[14:17], v162 offset:32064
	ds_read_b128 v[18:21], v162 offset:32128
	ds_read_b128 v[42:45], v162 offset:32192
	ds_read_b128 v[158:161], v162 offset:32256
	ds_read_b128 v[172:175], v162 offset:32320
	s_waitcnt lgkmcnt(5)
	v_mfma_f32_16x16x32_bf16 v[26:29], v[154:157], v[10:13], 0
	v_mfma_f32_16x16x32_bf16 v[34:37], v[22:25], v[10:13], 0
	v_mfma_f32_16x16x32_bf16 v[10:13], v[146:149], v[10:13], 0
	s_waitcnt lgkmcnt(4)
	v_mfma_f32_16x16x32_bf16 v[26:29], v[150:153], v[14:17], v[26:29]
	v_mfma_f32_16x16x32_bf16 v[34:37], v[98:101], v[14:17], v[34:37]
	v_mfma_f32_16x16x32_bf16 v[10:13], v[118:121], v[14:17], v[10:13]
	s_waitcnt lgkmcnt(3)
	v_mfma_f32_16x16x32_bf16 v[26:29], v[142:145], v[18:21], v[26:29]
	v_mfma_f32_16x16x32_bf16 v[34:37], v[102:105], v[18:21], v[34:37]
	v_mfma_f32_16x16x32_bf16 v[10:13], v[122:125], v[18:21], v[10:13]
	s_waitcnt lgkmcnt(2)
	v_mfma_f32_16x16x32_bf16 v[26:29], v[138:141], v[42:45], v[26:29]
	v_mfma_f32_16x16x32_bf16 v[34:37], v[106:109], v[42:45], v[34:37]
	v_mfma_f32_16x16x32_bf16 v[10:13], v[126:129], v[42:45], v[10:13]
	s_waitcnt lgkmcnt(1)
	v_mfma_f32_16x16x32_bf16 v[26:29], v[6:9], v[158:161], v[26:29]
	v_mfma_f32_16x16x32_bf16 v[34:37], v[110:113], v[158:161], v[34:37]
	v_mfma_f32_16x16x32_bf16 v[10:13], v[130:133], v[158:161], v[10:13]
	s_waitcnt lgkmcnt(0)
	v_mfma_f32_16x16x32_bf16 v[26:29], v[2:5], v[172:175], v[26:29]
	v_mfma_f32_16x16x32_bf16 v[34:37], v[114:117], v[172:175], v[34:37]
	v_mfma_f32_16x16x32_bf16 v[42:45], v[134:137], v[172:175], v[10:13]
	ds_read_b128 v[18:21], v162 offset:38400
	ds_read_b128 v[158:161], v162 offset:38464
	ds_read_b128 v[172:175], v162 offset:38528
	ds_read_b128 v[176:179], v162 offset:38592
	ds_read_b128 v[180:183], v162 offset:38656
	ds_read_b128 v[184:187], v162 offset:38720
	s_waitcnt lgkmcnt(5)
	v_mfma_f32_16x16x32_bf16 v[10:13], v[154:157], v[18:21], 0
	v_mfma_f32_16x16x32_bf16 v[14:17], v[22:25], v[18:21], 0
	v_mfma_f32_16x16x32_bf16 v[18:21], v[146:149], v[18:21], 0
	s_waitcnt lgkmcnt(4)
	v_mfma_f32_16x16x32_bf16 v[10:13], v[150:153], v[158:161], v[10:13]
	v_mfma_f32_16x16x32_bf16 v[14:17], v[98:101], v[158:161], v[14:17]
	v_mfma_f32_16x16x32_bf16 v[18:21], v[118:121], v[158:161], v[18:21]
	s_waitcnt lgkmcnt(3)
	v_mfma_f32_16x16x32_bf16 v[10:13], v[142:145], v[172:175], v[10:13]
	v_mfma_f32_16x16x32_bf16 v[14:17], v[102:105], v[172:175], v[14:17]
	v_mfma_f32_16x16x32_bf16 v[18:21], v[122:125], v[172:175], v[18:21]
	s_waitcnt lgkmcnt(2)
	v_mfma_f32_16x16x32_bf16 v[10:13], v[138:141], v[176:179], v[10:13]
	v_mfma_f32_16x16x32_bf16 v[14:17], v[106:109], v[176:179], v[14:17]
	v_mfma_f32_16x16x32_bf16 v[18:21], v[126:129], v[176:179], v[18:21]
	s_waitcnt lgkmcnt(1)
	v_mfma_f32_16x16x32_bf16 v[10:13], v[6:9], v[180:183], v[10:13]
	v_mfma_f32_16x16x32_bf16 v[14:17], v[110:113], v[180:183], v[14:17]
	v_mfma_f32_16x16x32_bf16 v[18:21], v[130:133], v[180:183], v[18:21]
	s_waitcnt lgkmcnt(0)
	v_mfma_f32_16x16x32_bf16 v[10:13], v[2:5], v[184:187], v[10:13]
	v_mfma_f32_16x16x32_bf16 v[14:17], v[114:117], v[184:187], v[14:17]
	v_mfma_f32_16x16x32_bf16 v[18:21], v[134:137], v[184:187], v[18:21]
	ds_read_b128 v[158:161], v162 offset:44800
	ds_read_b128 v[172:175], v162 offset:44864
	ds_read_b128 v[176:179], v162 offset:44928
	ds_read_b128 v[180:183], v162 offset:44992
	ds_read_b128 v[184:187], v162 offset:45056
	ds_read_b128 v[226:229], v162 offset:45120
	s_waitcnt lgkmcnt(5)
; __device__ __forceinline__ unsigned pk2(float lo, float hi) { unsigned r; asm("v_cvt_pk_bf16_f32 %0, %1, %2" : "=v"(r) : "v"(lo), "v"(hi)); return r; }
; __device__ __forceinline__ void mixer_chunk(KP p, LAS unsigned char* lds, int l, int chunk) {
;     ...
;         if (w & 1) {
; #pragma unroll
;             for (int mt = 0; mt < 8; ++mt) { const float* rt = (const float*)(ws + OFF_ROPE) + (size_t)(c0 + 16 * mt + fr) * 32 + 4 * fq; csn[2 * mt] = *(const u32x4*)rt; csn[2 * mt + 1] = *(const u32x4*)(rt + 16); }
;             pin(csn);
;         }
; #pragma unroll
;         for (int mt = 0; mt < 8; ++mt) {
;             const float rs = RSQ[16 * mt + fr];
;             f32x4 a0 = acc[mt][0] * rs, a1 = acc[mt][1] * rs, a2 = acc[mt][2] * rs;
;             if (w & 1) { const f32x4 cs = __builtin_bit_cast(f32x4, csn[2 * mt]), sn = __builtin_bit_cast(f32x4, csn[2 * mt + 1]); const f32x4 x1 = a1, x2 = a2; a1 = x1 * cs - x2 * sn; a2 = x2 * cs + x1 * sn; }
;             bf16_t* qd = (bf16_t*)(ws + OFF_Q) + ((size_t)(bidx * 4 + head) * SEQ + s0 + 16 * mt + fr) * 96 + d0 + 4 * fq;
;             u32x2 o; o.x = pk2(a0[0], a0[1]); o.y = pk2(a0[2], a0[3]); *(u32x2*)(qd) = o;
;             o.x = pk2(a1[0], a1[1]); o.y = pk2(a1[2], a1[3]); *(u32x2*)(qd + 16) = o;
;             o.x = pk2(a2[0], a2[1]); o.y = pk2(a2[2], a2[3]); *(u32x2*)(qd + 32) = o;
;         }
	v_mfma_f32_16x16x32_bf16 v[154:157], v[154:157], v[158:161], 0
	s_waitcnt lgkmcnt(4)
	v_mfma_f32_16x16x32_bf16 v[150:153], v[150:153], v[172:175], v[154:157]
	s_waitcnt lgkmcnt(3)
	v_mfma_f32_16x16x32_bf16 v[142:145], v[142:145], v[176:179], v[150:153]
	s_waitcnt lgkmcnt(2)
	v_mfma_f32_16x16x32_bf16 v[138:141], v[138:141], v[180:183], v[142:145]
	s_waitcnt lgkmcnt(1)
	v_mfma_f32_16x16x32_bf16 v[6:9], v[6:9], v[184:187], v[138:141]
	s_waitcnt lgkmcnt(0)
	v_mfma_f32_16x16x32_bf16 v[2:5], v[2:5], v[226:229], v[6:9]
	v_mfma_f32_16x16x32_bf16 v[6:9], v[22:25], v[158:161], 0
	v_mfma_f32_16x16x32_bf16 v[22:25], v[146:149], v[158:161], 0
	v_mfma_f32_16x16x32_bf16 v[6:9], v[98:101], v[172:175], v[6:9]
	v_mfma_f32_16x16x32_bf16 v[22:25], v[118:121], v[172:175], v[22:25]
	v_or_b32_e32 v174, 0x60, v168
	v_or_b32_e32 v172, 0x70, v168
	v_mfma_f32_16x16x32_bf16 v[6:9], v[102:105], v[176:179], v[6:9]
	v_mfma_f32_16x16x32_bf16 v[22:25], v[122:125], v[176:179], v[22:25]
	v_or_b32_e32 v178, 64, v168
	v_or_b32_e32 v176, 0x50, v168
	v_mfma_f32_16x16x32_bf16 v[6:9], v[106:109], v[180:183], v[6:9]
	v_mfma_f32_16x16x32_bf16 v[22:25], v[126:129], v[180:183], v[22:25]
	v_or_b32_e32 v182, 32, v168
	v_or_b32_e32 v180, 48, v168
	v_mfma_f32_16x16x32_bf16 v[6:9], v[110:113], v[184:187], v[6:9]
	v_mfma_f32_16x16x32_bf16 v[22:25], v[130:133], v[184:187], v[22:25]
	v_or_b32_e32 v184, 16, v168
	v_mfma_f32_16x16x32_bf16 v[6:9], v[114:117], v[226:229], v[6:9]
	v_mfma_f32_16x16x32_bf16 v[22:25], v[134:137], v[226:229], v[22:25]
	s_cbranch_vccnz .LBB0_318
	v_lshlrev_b32_e32 v98, 2, v221
	v_mov_b32_e32 v99, v1
	v_lshl_add_u64 v[98:99], s[92:93], 0, v[98:99]
	v_lshlrev_b64 v[100:101], 7, v[168:169]
	v_lshl_add_u64 v[100:101], v[98:99], 0, v[100:101]
	v_ashrrev_i32_e32 v185, 31, v184
	global_load_dwordx4 v[158:161], v[100:101], off
	global_load_dwordx4 v[154:157], v[100:101], off offset:64
	v_lshlrev_b64 v[100:101], 7, v[184:185]
	v_lshl_add_u64 v[100:101], v[98:99], 0, v[100:101]
	v_ashrrev_i32_e32 v183, 31, v182
	global_load_dwordx4 v[150:153], v[100:101], off
	global_load_dwordx4 v[146:149], v[100:101], off offset:64
	v_lshlrev_b64 v[100:101], 7, v[182:183]
	v_lshl_add_u64 v[100:101], v[98:99], 0, v[100:101]
	v_ashrrev_i32_e32 v181, 31, v180
	global_load_dwordx4 v[142:145], v[100:101], off
	global_load_dwordx4 v[138:141], v[100:101], off offset:64
	v_lshlrev_b64 v[100:101], 7, v[180:181]
	v_lshl_add_u64 v[100:101], v[98:99], 0, v[100:101]
	v_ashrrev_i32_e32 v179, 31, v178
	global_load_dwordx4 v[134:137], v[100:101], off
	global_load_dwordx4 v[130:133], v[100:101], off offset:64
	v_lshlrev_b64 v[100:101], 7, v[178:179]
	v_lshl_add_u64 v[100:101], v[98:99], 0, v[100:101]
	v_ashrrev_i32_e32 v177, 31, v176
	global_load_dwordx4 v[126:129], v[100:101], off
	global_load_dwordx4 v[122:125], v[100:101], off offset:64
	v_lshlrev_b64 v[100:101], 7, v[176:177]
	v_lshl_add_u64 v[100:101], v[98:99], 0, v[100:101]
	v_ashrrev_i32_e32 v175, 31, v174
	global_load_dwordx4 v[118:121], v[100:101], off
	global_load_dwordx4 v[114:117], v[100:101], off offset:64
	v_lshlrev_b64 v[100:101], 7, v[174:175]
	v_lshl_add_u64 v[100:101], v[98:99], 0, v[100:101]
	v_ashrrev_i32_e32 v173, 31, v172
	global_load_dwordx4 v[110:113], v[100:101], off
	global_load_dwordx4 v[106:109], v[100:101], off offset:64
	v_lshlrev_b64 v[100:101], 7, v[172:173]
	v_lshl_add_u64 v[98:99], v[98:99], 0, v[100:101]
	global_load_dwordx4 v[102:105], v[98:99], off
	s_nop 0
	global_load_dwordx4 v[98:101], v[98:99], off offset:64
	s_waitcnt vmcnt(0)
.LBB0_318:
	s_mul_i32 s6, s55, 3
	s_lshr_b32 s7, s55, 31
	s_add_i32 s7, s55, s7
	s_mul_hi_i32 s18, s6, 0x2aaaaaab
	v_lshlrev_b32_e32 v169, 2, v217
	s_ashr_i32 s7, s7, 1
	s_lshr_b32 s58, s18, 31
	v_add_u32_e32 v162, 0, v169
	s_add_i32 s18, s18, s58
	v_add_u32_e32 v162, 0x15000, v162
	s_add_i32 s60, s7, s96
	s_mul_i32 s18, s18, 6
	s_ashr_i32 s61, s60, 31
	ds_read2_b32 v[226:227], v162 offset1:16
	s_sub_i32 s6, s6, s18
	s_lshl_b64 s[60:61], s[60:61], 12
	s_lshl_b32 s6, s6, 4
	s_or_b32 s7, s60, s24
	v_or_b32_e32 v163, s7, v217
	s_ashr_i32 s7, s6, 31
	s_lshl_b64 s[6:7], s[6:7], 1
	v_readlane_b32 s18, v252, 10
	s_add_u32 s6, s18, s6
	v_readlane_b32 s18, v252, 11
	s_waitcnt lgkmcnt(0)
	v_pk_mul_f32 v[230:231], v[82:83], v[226:227] op_sel_hi:[1,0]
	v_pk_mul_f32 v[82:83], v[92:93], v[226:227] op_sel_hi:[1,0]
	v_pk_mul_f32 v[90:91], v[90:91], v[226:227] op_sel_hi:[1,0]
	v_pk_mul_f32 v[92:93], v[96:97], v[226:227] op_sel_hi:[1,0]
	v_pk_mul_f32 v[94:95], v[94:95], v[226:227] op_sel_hi:[1,0]
	s_addc_u32 s7, s18, s7
	v_lshlrev_b32_e32 v186, 1, v221
	v_mov_b32_e32 v187, v1
	v_pk_mul_f32 v[96:97], v[154:155], v[94:95]
	v_pk_mul_f32 v[232:233], v[156:157], v[92:93]
	v_pk_mul_f32 v[154:155], v[154:155], v[90:91]
	v_lshl_add_u64 v[228:229], s[6:7], 0, v[186:187]
	v_pk_fma_f32 v[232:233], v[160:161], v[82:83], v[232:233] neg_lo:[0,0,1] neg_hi:[0,0,1]
	v_pk_fma_f32 v[154:155], v[158:159], v[94:95], v[154:155]
	v_pk_mul_f32 v[84:85], v[84:85], v[226:227] op_sel_hi:[1,0]
	v_pk_fma_f32 v[96:97], v[158:159], v[90:91], v[96:97] neg_lo:[0,0,1] neg_hi:[0,0,1]
	v_pk_mul_f32 v[156:157], v[156:157], v[82:83]
	v_cndmask_b32_e64 v94, v154, v94, s[42:43]
	v_cndmask_b32_e64 v95, v155, v95, s[42:43]
	v_cndmask_b32_e64 v154, v232, v82, s[42:43]
	v_cndmask_b32_e64 v155, v233, v83, s[42:43]
	v_mad_u64_u32 v[82:83], s[6:7], v163, s57, v[228:229]
	v_cndmask_b32_e64 v96, v96, v90, s[42:43]
	v_cndmask_b32_e64 v97, v97, v91, s[42:43]
	v_mad_i32_i24 v83, s61, v195, v83
	v_cvt_pk_bf16_f32 v91, v84, v85
	v_cvt_pk_bf16_f32 v84, v96, v97
	v_pk_fma_f32 v[156:157], v[160:161], v[92:93], v[156:157]
	v_cvt_pk_bf16_f32 v85, v154, v155
	s_nop 1
; __device__ __forceinline__ unsigned pk2(float lo, float hi) { unsigned r; asm("v_cvt_pk_bf16_f32 %0, %1, %2" : "=v"(r) : "v"(lo), "v"(hi)); return r; }
; __device__ __forceinline__ void mixer_chunk(KP p, LAS unsigned char* lds, int l, int chunk) {
;     ...
; #pragma unroll
;         for (int mt = 0; mt < 8; ++mt) {
;             const float rs = RSQ[16 * mt + fr];
;             f32x4 a0 = acc[mt][0] * rs, a1 = acc[mt][1] * rs, a2 = acc[mt][2] * rs;
;             if (w & 1) { const f32x4 cs = __builtin_bit_cast(f32x4, csn[2 * mt]), sn = __builtin_bit_cast(f32x4, csn[2 * mt + 1]); const f32x4 x1 = a1, x2 = a2; a1 = x1 * cs - x2 * sn; a2 = x2 * cs + x1 * sn; }
;             bf16_t* qd = (bf16_t*)(ws + OFF_Q) + ((size_t)(bidx * 4 + head) * SEQ + s0 + 16 * mt + fr) * 96 + d0 + 4 * fq;
;             u32x2 o; o.x = pk2(a0[0], a0[1]); o.y = pk2(a0[2], a0[3]); *(u32x2*)(qd) = o;
;             o.x = pk2(a1[0], a1[1]); o.y = pk2(a1[2], a1[3]); *(u32x2*)(qd + 16) = o;
;             o.x = pk2(a2[0], a2[1]); o.y = pk2(a2[2], a2[3]); *(u32x2*)(qd + 32) = o;
;         }
	v_mov_b32_e32 v244, v84
	v_mov_b32_e32 v245, v85
	v_cvt_pk_bf16_f32 v84, v94, v95
	v_cndmask_b32_e64 v92, v156, v92, s[42:43]
	v_cndmask_b32_e64 v93, v157, v93, s[42:43]
	v_cvt_pk_bf16_f32 v85, v92, v93
	v_mov_b32_e32 v246, v84
	v_mov_b32_e32 v247, v85
	v_bfe_u32 v248, v193, 4, 1
	v_mul_u32_u24_e32 v248, 24, v248
	v_add_co_u32_e64 v248, s[98:99], v248, v82
	s_nop 1
	v_addc_co_u32_e64 v249, s[98:99], 0, v83, s[98:99]
	v_permlane16_swap_b32_e32 v244, v246
	v_permlane16_swap_b32_e32 v245, v247
	global_store_dwordx4 v[248:249], v[244:247], off offset:32
	v_mov_b32_e32 v84, v227
	v_pk_mul_f32 v[76:77], v[76:77], v[84:85] op_sel_hi:[1,0]
	v_pk_mul_f32 v[74:75], v[74:75], v[84:85] op_sel_hi:[1,0]
	v_cvt_pk_bf16_f32 v90, v230, v231
	v_pk_mul_f32 v[80:81], v[80:81], v[84:85] op_sel_hi:[1,0]
	v_cvt_pk_bf16_f32 v74, v74, v75
	v_cvt_pk_bf16_f32 v75, v76, v77
	ds_read2_b32 v[76:77], v162 offset0:32 offset1:48
	v_pk_mul_f32 v[78:79], v[78:79], v[84:85] op_sel_hi:[1,0]
	v_pk_mul_f32 v[88:89], v[88:89], v[84:85] op_sel_hi:[1,0]
	v_pk_mul_f32 v[84:85], v[86:87], v[84:85] op_sel_hi:[1,0]
	global_store_dwordx2 v[82:83], v[90:91], off
	v_pk_mul_f32 v[86:87], v[146:147], v[84:85]
	v_pk_mul_f32 v[90:91], v[148:149], v[88:89]
	v_pk_fma_f32 v[86:87], v[150:151], v[78:79], v[86:87] neg_lo:[0,0,1] neg_hi:[0,0,1]
	v_pk_fma_f32 v[90:91], v[152:153], v[80:81], v[90:91] neg_lo:[0,0,1] neg_hi:[0,0,1]
	v_pk_mul_f32 v[92:93], v[146:147], v[78:79]
	v_pk_mul_f32 v[94:95], v[148:149], v[80:81]
	v_pk_fma_f32 v[92:93], v[150:151], v[84:85], v[92:93]
	v_pk_fma_f32 v[94:95], v[152:153], v[88:89], v[94:95]
	v_cndmask_b32_e64 v80, v90, v80, s[42:43]
	v_cndmask_b32_e64 v81, v91, v81, s[42:43]
	v_cndmask_b32_e64 v78, v86, v78, s[42:43]
	v_cndmask_b32_e64 v79, v87, v79, s[42:43]
	s_nop 1
	v_mov_b32_e32 v244, v74
	v_mov_b32_e32 v245, v75
	v_cvt_pk_bf16_f32 v74, v78, v79
	v_cvt_pk_bf16_f32 v75, v80, v81
	v_cndmask_b32_e64 v88, v94, v88, s[42:43]
	v_cndmask_b32_e64 v89, v95, v89, s[42:43]
	v_cndmask_b32_e64 v84, v92, v84, s[42:43]
	v_cndmask_b32_e64 v85, v93, v85, s[42:43]
	v_mov_b32_e32 v246, v74
	v_mov_b32_e32 v247, v75
	v_bfe_u32 v248, v193, 4, 1
	v_mul_u32_u24_e32 v248, 24, v248
	v_add_co_u32_e64 v248, s[98:99], v248, v82
	s_nop 1
	v_addc_co_u32_e64 v249, s[98:99], 0, v83, s[98:99]
	v_permlane16_swap_b32_e32 v244, v246
	v_permlane16_swap_b32_e32 v245, v247
	global_store_dwordx4 v[248:249], v[244:247], off offset:3072
	v_cvt_pk_bf16_f32 v74, v84, v85
	v_cvt_pk_bf16_f32 v75, v88, v89
	s_waitcnt lgkmcnt(0)
	v_pk_mul_f32 v[64:65], v[64:65], v[76:77] op_sel_hi:[1,0]
	v_pk_mul_f32 v[62:63], v[62:63], v[76:77] op_sel_hi:[1,0]
	v_pk_mul_f32 v[70:71], v[70:71], v[76:77] op_sel_hi:[1,0]
	s_movk_i32 s6, 0x1000
	global_store_dwordx2 v[82:83], v[74:75], off offset:3136
	v_pk_mul_f32 v[66:67], v[66:67], v[76:77] op_sel_hi:[1,0]
	v_pk_mul_f32 v[72:73], v[72:73], v[76:77] op_sel_hi:[1,0]
	v_pk_mul_f32 v[74:75], v[138:139], v[70:71]
	v_cvt_pk_bf16_f32 v62, v62, v63
	v_cvt_pk_bf16_f32 v63, v64, v65
	v_add_co_u32_e32 v64, vcc, s6, v82
	v_pk_mul_f32 v[68:69], v[68:69], v[76:77] op_sel_hi:[1,0]
	v_pk_mul_f32 v[78:79], v[140:141], v[72:73]
	v_pk_fma_f32 v[74:75], v[142:143], v[66:67], v[74:75] neg_lo:[0,0,1] neg_hi:[0,0,1]
	v_pk_mul_f32 v[80:81], v[138:139], v[66:67]
	v_addc_co_u32_e32 v65, vcc, 0, v83, vcc
	v_pk_fma_f32 v[78:79], v[144:145], v[68:69], v[78:79] neg_lo:[0,0,1] neg_hi:[0,0,1]
	v_pk_mul_f32 v[84:85], v[140:141], v[68:69]
	v_pk_fma_f32 v[80:81], v[142:143], v[70:71], v[80:81]
	v_cndmask_b32_e64 v66, v74, v66, s[42:43]
	v_cndmask_b32_e64 v67, v75, v67, s[42:43]
	s_nop 1
	v_mov_b32_e32 v244, v62
	v_mov_b32_e32 v245, v63
	v_cvt_pk_bf16_f32 v62, v66, v67
	v_pk_fma_f32 v[84:85], v[144:145], v[72:73], v[84:85]
	v_cndmask_b32_e64 v70, v80, v70, s[42:43]
	v_cndmask_b32_e64 v71, v81, v71, s[42:43]
	v_cndmask_b32_e64 v68, v78, v68, s[42:43]
	v_cndmask_b32_e64 v69, v79, v69, s[42:43]
	v_cvt_pk_bf16_f32 v63, v68, v69
	v_mov_b32_e32 v246, v62
	v_mov_b32_e32 v247, v63
	v_bfe_u32 v248, v193, 4, 1
	v_mul_u32_u24_e32 v248, 24, v248
	v_add_co_u32_e64 v248, s[98:99], v248, v64
	s_nop 1
	v_addc_co_u32_e64 v249, s[98:99], 0, v65, s[98:99]
	v_permlane16_swap_b32_e32 v244, v246
	v_permlane16_swap_b32_e32 v245, v247
	global_store_dwordx4 v[248:249], v[244:247], off offset:2048
	v_cvt_pk_bf16_f32 v62, v70, v71
	v_cndmask_b32_e64 v72, v84, v72, s[42:43]
	v_cndmask_b32_e64 v73, v85, v73, s[42:43]
	v_cvt_pk_bf16_f32 v63, v72, v73
	global_store_dwordx2 v[64:65], v[62:63], off offset:2112
	v_mov_b32_e32 v62, v77
	v_pk_mul_f32 v[58:59], v[58:59], v[62:63] op_sel_hi:[1,0]
	v_pk_mul_f32 v[52:53], v[52:53], v[62:63] op_sel_hi:[1,0]
	v_pk_mul_f32 v[50:51], v[50:51], v[62:63] op_sel_hi:[1,0]
	v_pk_mul_f32 v[56:57], v[56:57], v[62:63] op_sel_hi:[1,0]
	v_pk_mul_f32 v[54:55], v[54:55], v[62:63] op_sel_hi:[1,0]
	v_pk_mul_f32 v[60:61], v[60:61], v[62:63] op_sel_hi:[1,0]
	v_pk_mul_f32 v[62:63], v[130:131], v[58:59]
	v_cvt_pk_bf16_f32 v50, v50, v51
	v_cvt_pk_bf16_f32 v51, v52, v53
	v_add_co_u32_e32 v52, vcc, s39, v82
	v_pk_fma_f32 v[62:63], v[134:135], v[54:55], v[62:63] neg_lo:[0,0,1] neg_hi:[0,0,1]
	v_pk_mul_f32 v[66:67], v[130:131], v[54:55]
	v_cndmask_b32_e64 v54, v62, v54, s[42:43]
	v_cndmask_b32_e64 v55, v63, v55, s[42:43]
	v_addc_co_u32_e32 v53, vcc, 0, v83, vcc
	global_store_dwordx2 v[52:53], v[50:51], off offset:1024
	v_cvt_pk_bf16_f32 v50, v54, v55
	ds_read2_b32 v[54:55], v162 offset0:64 offset1:80
	v_pk_mul_f32 v[64:65], v[132:133], v[60:61]
	v_pk_mul_f32 v[68:69], v[132:133], v[56:57]
	v_pk_fma_f32 v[64:65], v[136:137], v[56:57], v[64:65] neg_lo:[0,0,1] neg_hi:[0,0,1]
	v_pk_fma_f32 v[68:69], v[136:137], v[60:61], v[68:69]
	v_pk_fma_f32 v[66:67], v[134:135], v[58:59], v[66:67]
	v_cndmask_b32_e64 v56, v64, v56, s[42:43]
	v_cndmask_b32_e64 v57, v65, v57, s[42:43]
	v_cvt_pk_bf16_f32 v51, v56, v57
	v_cndmask_b32_e64 v60, v68, v60, s[42:43]
	v_cndmask_b32_e64 v61, v69, v61, s[42:43]
	v_cndmask_b32_e64 v58, v66, v58, s[42:43]
	v_cndmask_b32_e64 v59, v67, v59, s[42:43]
	s_nop 1
	v_mov_b32_e32 v244, v50
	v_mov_b32_e32 v245, v51
	v_cvt_pk_bf16_f32 v50, v58, v59
	v_cvt_pk_bf16_f32 v51, v60, v61
	s_waitcnt lgkmcnt(0)
; __device__ __forceinline__ unsigned pk2(float lo, float hi) { unsigned r; asm("v_cvt_pk_bf16_f32 %0, %1, %2" : "=v"(r) : "v"(lo), "v"(hi)); return r; }
; __device__ __forceinline__ void mixer_chunk(KP p, LAS unsigned char* lds, int l, int chunk) {
;     ...
;         for (int mt = 0; mt < 8; ++mt) {
;             const float rs = RSQ[16 * mt + fr];
;             f32x4 a0 = acc[mt][0] * rs, a1 = acc[mt][1] * rs, a2 = acc[mt][2] * rs;
;             if (w & 1) { const f32x4 cs = __builtin_bit_cast(f32x4, csn[2 * mt]), sn = __builtin_bit_cast(f32x4, csn[2 * mt + 1]); const f32x4 x1 = a1, x2 = a2; a1 = x1 * cs - x2 * sn; a2 = x2 * cs + x1 * sn; }
;             bf16_t* qd = (bf16_t*)(ws + OFF_Q) + ((size_t)(bidx * 4 + head) * SEQ + s0 + 16 * mt + fr) * 96 + d0 + 4 * fq;
;             u32x2 o; o.x = pk2(a0[0], a0[1]); o.y = pk2(a0[2], a0[3]); *(u32x2*)(qd) = o;
;             o.x = pk2(a1[0], a1[1]); o.y = pk2(a1[2], a1[3]); *(u32x2*)(qd + 16) = o;
;             o.x = pk2(a2[0], a2[1]); o.y = pk2(a2[2], a2[3]); *(u32x2*)(qd + 32) = o;
;         }
	v_pk_mul_f32 v[32:33], v[32:33], v[54:55] op_sel_hi:[1,0]
	v_pk_mul_f32 v[30:31], v[30:31], v[54:55] op_sel_hi:[1,0]
	v_pk_mul_f32 v[46:47], v[46:47], v[54:55] op_sel_hi:[1,0]
	v_mov_b32_e32 v246, v50
	v_mov_b32_e32 v247, v51
	v_bfe_u32 v248, v193, 4, 1
	v_mul_u32_u24_e32 v248, 24, v248
	v_add_co_u32_e64 v248, s[98:99], v248, v52
	s_nop 1
	v_addc_co_u32_e64 v249, s[98:99], 0, v53, s[98:99]
	v_permlane16_swap_b32_e32 v244, v246
	v_permlane16_swap_b32_e32 v245, v247
	global_store_dwordx4 v[248:249], v[244:247], off offset:1056
	v_pk_mul_f32 v[38:39], v[38:39], v[54:55] op_sel_hi:[1,0]
	v_pk_mul_f32 v[48:49], v[48:49], v[54:55] op_sel_hi:[1,0]
	v_pk_mul_f32 v[50:51], v[122:123], v[46:47]
	v_cvt_pk_bf16_f32 v30, v30, v31
	v_cvt_pk_bf16_f32 v31, v32, v33
	v_add_co_u32_e32 v32, vcc, s68, v82
	v_pk_mul_f32 v[40:41], v[40:41], v[54:55] op_sel_hi:[1,0]
	v_pk_mul_f32 v[52:53], v[124:125], v[48:49]
	v_pk_fma_f32 v[50:51], v[126:127], v[38:39], v[50:51] neg_lo:[0,0,1] neg_hi:[0,0,1]
	v_pk_mul_f32 v[56:57], v[122:123], v[38:39]
	v_addc_co_u32_e32 v33, vcc, 0, v83, vcc
	v_pk_fma_f32 v[52:53], v[128:129], v[40:41], v[52:53] neg_lo:[0,0,1] neg_hi:[0,0,1]
	v_pk_mul_f32 v[58:59], v[124:125], v[40:41]
	v_pk_fma_f32 v[56:57], v[126:127], v[46:47], v[56:57]
	v_cndmask_b32_e64 v38, v50, v38, s[42:43]
	v_cndmask_b32_e64 v39, v51, v39, s[42:43]
	s_nop 1
	v_mov_b32_e32 v244, v30
	v_mov_b32_e32 v245, v31
	v_cvt_pk_bf16_f32 v30, v38, v39
	v_pk_fma_f32 v[58:59], v[128:129], v[48:49], v[58:59]
	v_cndmask_b32_e64 v46, v56, v46, s[42:43]
	v_cndmask_b32_e64 v47, v57, v47, s[42:43]
	v_cndmask_b32_e64 v40, v52, v40, s[42:43]
	v_cndmask_b32_e64 v41, v53, v41, s[42:43]
	v_cvt_pk_bf16_f32 v31, v40, v41
	v_mov_b32_e32 v246, v30
	v_mov_b32_e32 v247, v31
	v_bfe_u32 v248, v193, 4, 1
	v_mul_u32_u24_e32 v248, 24, v248
	v_add_co_u32_e64 v248, s[98:99], v248, v32
	s_nop 1
	v_addc_co_u32_e64 v249, s[98:99], 0, v33, s[98:99]
	v_permlane16_swap_b32_e32 v244, v246
	v_permlane16_swap_b32_e32 v245, v247
	global_store_dwordx4 v[248:249], v[244:247], off
	v_cvt_pk_bf16_f32 v30, v46, v47
	v_cndmask_b32_e64 v48, v58, v48, s[42:43]
	v_cndmask_b32_e64 v49, v59, v49, s[42:43]
	v_cvt_pk_bf16_f32 v31, v48, v49
	global_store_dwordx2 v[32:33], v[30:31], off offset:64
	v_mov_b32_e32 v30, v55
	v_pk_mul_f32 v[28:29], v[28:29], v[30:31] op_sel_hi:[1,0]
	v_pk_mul_f32 v[26:27], v[26:27], v[30:31] op_sel_hi:[1,0]
	v_pk_mul_f32 v[36:37], v[36:37], v[30:31] op_sel_hi:[1,0]
	v_cvt_pk_bf16_f32 v26, v26, v27
	v_cvt_pk_bf16_f32 v27, v28, v29
	ds_read2_b32 v[28:29], v162 offset0:96 offset1:112
	v_pk_mul_f32 v[34:35], v[34:35], v[30:31] op_sel_hi:[1,0]
	v_pk_mul_f32 v[38:39], v[44:45], v[30:31] op_sel_hi:[1,0]
	v_pk_mul_f32 v[30:31], v[42:43], v[30:31] op_sel_hi:[1,0]
	v_pk_mul_f32 v[42:43], v[116:117], v[38:39]
	v_pk_mul_f32 v[40:41], v[114:115], v[30:31]
	v_pk_fma_f32 v[42:43], v[120:121], v[36:37], v[42:43] neg_lo:[0,0,1] neg_hi:[0,0,1]
	v_pk_fma_f32 v[40:41], v[118:119], v[34:35], v[40:41] neg_lo:[0,0,1] neg_hi:[0,0,1]
	v_pk_mul_f32 v[44:45], v[114:115], v[34:35]
	v_pk_mul_f32 v[46:47], v[116:117], v[36:37]
	v_pk_fma_f32 v[44:45], v[118:119], v[30:31], v[44:45]
	v_pk_fma_f32 v[46:47], v[120:121], v[38:39], v[46:47]
	v_cndmask_b32_e64 v36, v42, v36, s[42:43]
	v_cndmask_b32_e64 v37, v43, v37, s[42:43]
	v_cndmask_b32_e64 v34, v40, v34, s[42:43]
	v_cndmask_b32_e64 v35, v41, v35, s[42:43]
	s_nop 1
	v_mov_b32_e32 v244, v26
	v_mov_b32_e32 v245, v27
	v_cvt_pk_bf16_f32 v26, v34, v35
	v_cvt_pk_bf16_f32 v27, v36, v37
	v_cndmask_b32_e64 v38, v46, v38, s[42:43]
	v_cndmask_b32_e64 v39, v47, v39, s[42:43]
	v_cndmask_b32_e64 v30, v44, v30, s[42:43]
	v_cndmask_b32_e64 v31, v45, v31, s[42:43]
	v_mov_b32_e32 v246, v26
	v_mov_b32_e32 v247, v27
	v_bfe_u32 v248, v193, 4, 1
	v_mul_u32_u24_e32 v248, 24, v248
	v_add_co_u32_e64 v248, s[98:99], v248, v32
	s_nop 1
	v_addc_co_u32_e64 v249, s[98:99], 0, v33, s[98:99]
	v_permlane16_swap_b32_e32 v244, v246
	v_permlane16_swap_b32_e32 v245, v247
	global_store_dwordx4 v[248:249], v[244:247], off offset:3072
	v_cvt_pk_bf16_f32 v26, v30, v31
	v_cvt_pk_bf16_f32 v27, v38, v39
	s_waitcnt lgkmcnt(0)
; __device__ __forceinline__ unsigned pk2(float lo, float hi) { unsigned r; asm("v_cvt_pk_bf16_f32 %0, %1, %2" : "=v"(r) : "v"(lo), "v"(hi)); return r; }
; __device__ __forceinline__ void mixer_chunk(KP p, LAS unsigned char* lds, int l, int chunk) {
;     ...
;         for (int mt = 0; mt < 8; ++mt) {
;             const float rs = RSQ[16 * mt + fr];
;             f32x4 a0 = acc[mt][0] * rs, a1 = acc[mt][1] * rs, a2 = acc[mt][2] * rs;
;             if (w & 1) { const f32x4 cs = __builtin_bit_cast(f32x4, csn[2 * mt]), sn = __builtin_bit_cast(f32x4, csn[2 * mt + 1]); const f32x4 x1 = a1, x2 = a2; a1 = x1 * cs - x2 * sn; a2 = x2 * cs + x1 * sn; }
;             bf16_t* qd = (bf16_t*)(ws + OFF_Q) + ((size_t)(bidx * 4 + head) * SEQ + s0 + 16 * mt + fr) * 96 + d0 + 4 * fq;
;             u32x2 o; o.x = pk2(a0[0], a0[1]); o.y = pk2(a0[2], a0[3]); *(u32x2*)(qd) = o;
;             o.x = pk2(a1[0], a1[1]); o.y = pk2(a1[2], a1[3]); *(u32x2*)(qd + 16) = o;
;             o.x = pk2(a2[0], a2[1]); o.y = pk2(a2[2], a2[3]); *(u32x2*)(qd + 32) = o;
;         }
;     }
; #pragma unroll 1
;     for (int pz = 0; pz < 2; ++pz) {
;         f32x4 acc[8][2];
;         wgemm<4, 2>(acc, CK + fr * CKLD + 8 * fq, CKLD, (const bf16_t*)(ws + OFF_UKV + l * SZ_UKV) + (size_t)(64 * w + 32 * pz + fr) * 128 + 8 * fq, 128);
;         const int head = w >> 1;
; #pragma unroll
;         for (int mt = 0; mt < 8; ++mt) {
;             const float rs = RSK[16 * mt + fr]; const int spos = s0 + 16 * mt + fr;
; #pragma unroll
;             for (int n = 0; n < 2; ++n) {
;                 const f32x4 a = acc[mt][n] * rs; const unsigned p0 = pk2(a[0], a[1]), p1 = pk2(a[2], a[3]);
;                 if ((w & 1) == 0) { u32x2 o; o.x = p0; o.y = p1; *(u32x2*)((bf16_t*)(ws + OFF_K) + ((size_t)(bidx * 4 + head) * SEQ + spos) * 96 + 16 * (2 * pz + n) + 4 * fq) = o; }
;                 else { const int fp = ((fr & 4) << 1) | ((fr & 8) >> 1) | (fr & 3);
;                     bf16_t* vv = (bf16_t*)(ws + OFF_VT) + ((size_t)(bidx * 4 + head) * 64 + 16 * (2 * pz + n) + 4 * fq) * SEQ + (spos - fr + fp);
;                     vv[0] = (bf16_t)(p0 & 0xffff); vv[SEQ] = (bf16_t)(p0 >> 16); vv[2 * SEQ] = (bf16_t)(p1 & 0xffff); vv[3 * SEQ] = (bf16_t)(p1 >> 16); }
	v_pk_mul_f32 v[12:13], v[12:13], v[28:29] op_sel_hi:[1,0]
	v_pk_mul_f32 v[10:11], v[10:11], v[28:29] op_sel_hi:[1,0]
	v_pk_mul_f32 v[18:19], v[18:19], v[28:29] op_sel_hi:[1,0]
	s_movk_i32 s6, 0x4000
	global_store_dwordx2 v[32:33], v[26:27], off offset:3136
	v_pk_mul_f32 v[14:15], v[14:15], v[28:29] op_sel_hi:[1,0]
	v_pk_mul_f32 v[20:21], v[20:21], v[28:29] op_sel_hi:[1,0]
	v_pk_mul_f32 v[26:27], v[106:107], v[18:19]
	v_cvt_pk_bf16_f32 v10, v10, v11
	v_cvt_pk_bf16_f32 v11, v12, v13
	v_add_co_u32_e32 v12, vcc, s6, v82
	v_pk_mul_f32 v[16:17], v[16:17], v[28:29] op_sel_hi:[1,0]
	v_pk_mul_f32 v[30:31], v[108:109], v[20:21]
	v_pk_fma_f32 v[26:27], v[110:111], v[14:15], v[26:27] neg_lo:[0,0,1] neg_hi:[0,0,1]
	v_pk_mul_f32 v[32:33], v[106:107], v[14:15]
	v_addc_co_u32_e32 v13, vcc, 0, v83, vcc
	v_pk_fma_f32 v[30:31], v[112:113], v[16:17], v[30:31] neg_lo:[0,0,1] neg_hi:[0,0,1]
	v_pk_mul_f32 v[34:35], v[108:109], v[16:17]
	v_pk_fma_f32 v[32:33], v[110:111], v[18:19], v[32:33]
	v_cndmask_b32_e64 v14, v26, v14, s[42:43]
	v_cndmask_b32_e64 v15, v27, v15, s[42:43]
	s_nop 1
	v_mov_b32_e32 v244, v10
	v_mov_b32_e32 v245, v11
	v_cvt_pk_bf16_f32 v10, v14, v15
	v_pk_fma_f32 v[34:35], v[112:113], v[20:21], v[34:35]
	v_cndmask_b32_e64 v18, v32, v18, s[42:43]
	v_cndmask_b32_e64 v19, v33, v19, s[42:43]
	v_cndmask_b32_e64 v16, v30, v16, s[42:43]
	v_cndmask_b32_e64 v17, v31, v17, s[42:43]
	v_cvt_pk_bf16_f32 v11, v16, v17
	v_mov_b32_e32 v246, v10
	v_mov_b32_e32 v247, v11
	v_bfe_u32 v248, v193, 4, 1
	v_mul_u32_u24_e32 v248, 24, v248
	v_add_co_u32_e64 v248, s[98:99], v248, v12
	s_nop 1
	v_addc_co_u32_e64 v249, s[98:99], 0, v13, s[98:99]
	v_permlane16_swap_b32_e32 v244, v246
	v_permlane16_swap_b32_e32 v245, v247
	global_store_dwordx4 v[248:249], v[244:247], off offset:2048
	v_cvt_pk_bf16_f32 v10, v18, v19
	v_cndmask_b32_e64 v20, v34, v20, s[42:43]
	v_cndmask_b32_e64 v21, v35, v21, s[42:43]
	v_cvt_pk_bf16_f32 v11, v20, v21
	global_store_dwordx2 v[12:13], v[10:11], off offset:2112
	v_mov_b32_e32 v10, v29
	v_pk_mul_f32 v[4:5], v[4:5], v[10:11] op_sel_hi:[1,0]
	v_pk_mul_f32 v[2:3], v[2:3], v[10:11] op_sel_hi:[1,0]
	v_pk_mul_f32 v[8:9], v[8:9], v[10:11] op_sel_hi:[1,0]
	v_pk_mul_f32 v[6:7], v[6:7], v[10:11] op_sel_hi:[1,0]
	v_pk_mul_f32 v[12:13], v[24:25], v[10:11] op_sel_hi:[1,0]
	v_pk_mul_f32 v[10:11], v[22:23], v[10:11] op_sel_hi:[1,0]
	s_movk_i32 s6, 0x5000
	v_pk_mul_f32 v[14:15], v[98:99], v[10:11]
	v_cvt_pk_bf16_f32 v2, v2, v3
	v_cvt_pk_bf16_f32 v3, v4, v5
	v_add_co_u32_e32 v4, vcc, s6, v82
	v_pk_mul_f32 v[16:17], v[100:101], v[12:13]
	v_pk_fma_f32 v[14:15], v[102:103], v[6:7], v[14:15] neg_lo:[0,0,1] neg_hi:[0,0,1]
	v_pk_mul_f32 v[18:19], v[98:99], v[6:7]
	v_addc_co_u32_e32 v5, vcc, 0, v83, vcc
	v_pk_fma_f32 v[16:17], v[104:105], v[8:9], v[16:17] neg_lo:[0,0,1] neg_hi:[0,0,1]
	v_pk_mul_f32 v[20:21], v[100:101], v[8:9]
	v_pk_fma_f32 v[18:19], v[102:103], v[10:11], v[18:19]
	v_cndmask_b32_e64 v6, v14, v6, s[42:43]
	v_cndmask_b32_e64 v7, v15, v7, s[42:43]
	s_nop 1
	v_mov_b32_e32 v244, v2
	v_mov_b32_e32 v245, v3
	v_cvt_pk_bf16_f32 v2, v6, v7
	v_pk_fma_f32 v[20:21], v[104:105], v[12:13], v[20:21]
	v_cndmask_b32_e64 v10, v18, v10, s[42:43]
	v_cndmask_b32_e64 v11, v19, v11, s[42:43]
	v_cndmask_b32_e64 v8, v16, v8, s[42:43]
	v_cndmask_b32_e64 v9, v17, v9, s[42:43]
	v_cvt_pk_bf16_f32 v3, v8, v9
	v_mov_b32_e32 v246, v2
	v_mov_b32_e32 v247, v3
	v_bfe_u32 v248, v193, 4, 1
	v_mul_u32_u24_e32 v248, 24, v248
	v_add_co_u32_e64 v248, s[98:99], v248, v4
	s_nop 1
	v_addc_co_u32_e64 v249, s[98:99], 0, v5, s[98:99]
	v_permlane16_swap_b32_e32 v244, v246
	v_permlane16_swap_b32_e32 v245, v247
	global_store_dwordx4 v[248:249], v[244:247], off offset:1024
	v_cvt_pk_bf16_f32 v2, v10, v11
	v_cndmask_b32_e64 v12, v20, v12, s[42:43]
	v_cndmask_b32_e64 v13, v21, v13, s[42:43]
	v_cvt_pk_bf16_f32 v3, v12, v13
	global_store_dwordx2 v[4:5], v[2:3], off offset:1088
	v_mul_u32_u24_e32 v2, 0x110, v217
	v_add3_u32 v104, 0, v2, v0
	s_and_b32 s6, s54, 0xffffffc0
	v_lshlrev_b32_e32 v2, 1, v204
	v_lshrrev_b32_e32 v3, 1, v204
	v_or_b32_e32 v106, s6, v217
	s_add_i32 s6, 0, 0x15200
	v_and_b32_e32 v2, 8, v2
	v_and_b32_e32 v3, 4, v3
	v_and_b32_e32 v4, 3, v204
	v_add_u32_e32 v107, s6, v169
	s_add_i32 s6, s47, s96
	v_or3_b32 v6, v3, v4, v2
	s_ashr_i32 s7, s6, 31
	v_or_b32_e32 v4, s24, v6
	s_lshl_b64 s[42:43], s[6:7], 6
	s_lshl_b64 s[6:7], s[6:7], 12
	v_or_b32_e32 v7, s24, v217
	v_lshlrev_b32_e32 v4, 1, v4
	v_mov_b32_e32 v5, v1
	v_lshl_add_u64 v[2:3], s[12:13], 0, v[186:187]
	v_lshl_add_u64 v[66:67], s[8:9], 0, v[4:5]
	v_or_b32_e32 v4, s6, v7
	v_mov_b32_e32 v65, s43
	v_or_b32_e32 v64, s42, v221
	v_mad_u64_u32 v[68:69], s[42:43], v4, s57, v[2:3]
	s_or_b32 s42, s24, 16
	s_nop 0
	v_or_b32_e32 v4, s42, v217
	v_or_b32_e32 v4, s6, v4
	v_or_b32_e32 v5, s42, v6
	v_mad_u64_u32 v[70:71], s[42:43], v4, s57, v[2:3]
	s_or_b32 s42, s24, 32
	s_nop 0
	v_or_b32_e32 v4, s42, v217
	v_or_b32_e32 v4, s6, v4
	v_or_b32_e32 v7, s42, v6
	v_mad_u64_u32 v[72:73], s[42:43], v4, s57, v[2:3]
	s_or_b32 s42, s24, 48
	s_nop 0
	v_or_b32_e32 v4, s42, v217
	v_or_b32_e32 v4, s6, v4
	v_or_b32_e32 v8, s42, v6
	v_mad_u64_u32 v[74:75], s[42:43], v4, s57, v[2:3]
	s_or_b32 s42, s24, 64
	s_nop 0
	v_or_b32_e32 v4, s42, v217
	v_or_b32_e32 v4, s6, v4
	v_or_b32_e32 v9, s42, v6
	v_mad_u64_u32 v[76:77], s[42:43], v4, s57, v[2:3]
	s_or_b32 s42, s24, 0x50
	s_nop 0
	v_or_b32_e32 v4, s42, v217
	v_or_b32_e32 v4, s6, v4
	v_or_b32_e32 v10, s42, v6
	v_mad_u64_u32 v[78:79], s[42:43], v4, s57, v[2:3]
	s_or_b32 s42, s24, 0x60
	s_nop 0
	v_or_b32_e32 v4, s42, v217
	v_or_b32_e32 v4, s6, v4
	v_or_b32_e32 v11, s42, v6
	v_mad_u64_u32 v[80:81], s[42:43], v4, s57, v[2:3]
	s_or_b32 s42, s24, 0x70
	s_nop 0
	v_or_b32_e32 v4, s42, v217
	v_or_b32_e32 v4, s6, v4
	v_or_b32_e32 v6, s42, v6
	v_mad_u64_u32 v[82:83], s[42:43], v4, s57, v[2:3]
	v_lshlrev_b32_e32 v2, 1, v5
	v_mov_b32_e32 v3, v1
	v_lshl_add_u64 v[84:85], s[8:9], 0, v[2:3]
	v_lshlrev_b32_e32 v2, 1, v7
	v_lshl_add_u64 v[86:87], s[8:9], 0, v[2:3]
	v_lshlrev_b32_e32 v2, 1, v8
	v_lshl_add_u64 v[88:89], s[8:9], 0, v[2:3]
	v_lshlrev_b32_e32 v2, 1, v9
	v_lshl_add_u64 v[90:91], s[8:9], 0, v[2:3]
	v_lshlrev_b32_e32 v2, 1, v10
	v_lshl_add_u64 v[92:93], s[8:9], 0, v[2:3]
	v_lshlrev_b32_e32 v2, 1, v11
	v_lshl_add_u64 v[94:95], s[8:9], 0, v[2:3]
	v_lshlrev_b32_e32 v2, 1, v6
	s_mov_b32 s18, 0
	v_add_u32_e32 v105, 0xc800, v104
	v_lshl_add_u64 v[62:63], s[84:85], 0, v[0:1]
	v_mad_i32_i24 v69, s7, v195, v69
	v_mad_i32_i24 v71, s7, v195, v71
	v_mad_i32_i24 v73, s7, v195, v73
	v_mad_i32_i24 v75, s7, v195, v75
	v_mad_i32_i24 v77, s7, v195, v77
	v_mad_i32_i24 v79, s7, v195, v79
	v_mad_i32_i24 v81, s7, v195, v81
	v_mad_i32_i24 v83, s7, v195, v83
	v_lshl_add_u64 v[96:97], s[8:9], 0, v[2:3]
	s_mov_b64 s[96:97], -1
	s_branch .LBB0_320

; __device__ __forceinline__ float rsq(float x) { return __builtin_amdgcn_rsqf(x); }
; __device__ __forceinline__ void mixer_chunk(KP p, LAS unsigned char* lds, int l, int chunk) {
;     ...
;     {
;         pin(vv);
;         const int j = 16 * w + (lane >> 2), q4 = lane & 3; float ss = 0.f;
; #pragma unroll
;         for (int i = 0; i < 8; ++i) ss += sumsq8(vv[i]);
;         ss += __shfl_xor(ss, 1); ss += __shfl_xor(ss, 2);
;         const float rs = rsq(ss * (1.0f / 256.0f) + EPS);
.LBB0_418:
	s_or_b64 exec, exec, s[6:7]
	s_load_dwordx2 s[6:7], s[0:1], 0x78
	s_load_dwordx2 s[96:97], s[0:1], 0x88
	v_and_b32_e32 v139, 0xffff0000, v94
	v_and_b32_e32 v141, 0xffff0000, v95
	v_and_b32_e32 v131, 0xffff0000, v90
	v_and_b32_e32 v128, 0xffff0000, v91
	v_lshlrev_b32_e32 v138, 16, v94
	v_mul_f32_e32 v94, v139, v139
	v_lshlrev_b32_e32 v140, 16, v95
	v_mul_f32_e32 v95, v141, v141
	v_lshlrev_b32_e32 v132, 16, v90
	v_mul_f32_e32 v90, v131, v131
	v_lshlrev_b32_e32 v130, 16, v91
	v_mul_f32_e32 v91, v128, v128
	v_fmac_f32_e32 v94, v138, v138
	v_fmac_f32_e32 v95, v140, v140
	v_and_b32_e32 v143, 0xffff0000, v96
	v_fmac_f32_e32 v90, v132, v132
	v_fmac_f32_e32 v91, v130, v130
	v_and_b32_e32 v126, 0xffff0000, v92
	v_and_b32_e32 v122, 0xffff0000, v86
	v_and_b32_e32 v119, 0xffff0000, v87
	v_add_f32_e32 v94, v94, v95
	v_lshlrev_b32_e32 v142, 16, v96
	v_mul_f32_e32 v95, v143, v143
	v_add_f32_e32 v90, v90, v91
	v_lshlrev_b32_e32 v129, 16, v92
	v_mul_f32_e32 v91, v126, v126
	v_lshlrev_b32_e32 v123, 16, v86
	v_mul_f32_e32 v86, v122, v122
	v_lshlrev_b32_e32 v121, 16, v87
	v_mul_f32_e32 v87, v119, v119
	v_and_b32_e32 v114, 0xffff0000, v82
	v_and_b32_e32 v111, 0xffff0000, v83
	v_fmac_f32_e32 v95, v142, v142
	v_and_b32_e32 v145, 0xffff0000, v97
	v_fmac_f32_e32 v91, v129, v129
	v_and_b32_e32 v125, 0xffff0000, v93
	v_fmac_f32_e32 v86, v123, v123
	v_fmac_f32_e32 v87, v121, v121
	v_and_b32_e32 v117, 0xffff0000, v88
	v_lshlrev_b32_e32 v115, 16, v82
	v_mul_f32_e32 v82, v114, v114
	v_lshlrev_b32_e32 v113, 16, v83
	v_mul_f32_e32 v83, v111, v111
	v_add_f32_e32 v94, v95, v94
	v_lshlrev_b32_e32 v144, 16, v97
	v_mul_f32_e32 v95, v145, v145
	v_add_f32_e32 v90, v91, v90
	v_lshlrev_b32_e32 v127, 16, v93
	v_mul_f32_e32 v91, v125, v125
	v_add_f32_e32 v86, v86, v87
	v_lshlrev_b32_e32 v120, 16, v88
	v_mul_f32_e32 v87, v117, v117
	v_fmac_f32_e32 v82, v115, v115
	v_fmac_f32_e32 v83, v113, v113
	v_and_b32_e32 v109, 0xffff0000, v84
	v_fmac_f32_e32 v95, v144, v144
	v_fmac_f32_e32 v91, v127, v127
	v_fmac_f32_e32 v87, v120, v120
	v_and_b32_e32 v116, 0xffff0000, v89
	v_add_f32_e32 v82, v82, v83
	v_lshlrev_b32_e32 v112, 16, v84
	v_mul_f32_e32 v83, v109, v109
	v_and_b32_e32 v106, 0xffff0000, v78
	s_waitcnt lgkmcnt(0)
	v_and_b32_e32 v103, 0xffff0000, v79
	v_add_f32_e32 v94, v95, v94
	v_add_f32_e32 v90, v91, v90
	v_add_f32_e32 v86, v87, v86
	v_lshlrev_b32_e32 v118, 16, v89
	v_mul_f32_e32 v87, v116, v116
	v_fmac_f32_e32 v83, v112, v112
	v_and_b32_e32 v108, 0xffff0000, v85
	v_lshlrev_b32_e32 v107, 16, v78
	v_mul_f32_e32 v78, v106, v106
	v_lshlrev_b32_e32 v105, 16, v79
	v_mul_f32_e32 v79, v103, v103
	v_and_b32_e32 v95, 0xffff0000, v74
	v_and_b32_e32 v93, 0xffff0000, v75
	v_add_f32_e32 v90, v94, v90
	v_fmac_f32_e32 v87, v118, v118
	v_add_f32_e32 v82, v83, v82
	v_lshlrev_b32_e32 v110, 16, v85
	v_mul_f32_e32 v83, v108, v108
	v_fmac_f32_e32 v78, v107, v107
	v_fmac_f32_e32 v79, v105, v105
	v_and_b32_e32 v101, 0xffff0000, v80
	v_lshlrev_b32_e32 v96, 16, v74
	v_mul_f32_e32 v74, v95, v95
	v_lshlrev_b32_e32 v94, 16, v75
	v_mul_f32_e32 v75, v93, v93
	v_add_f32_e32 v86, v87, v86
	v_fmac_f32_e32 v83, v110, v110
	v_add_f32_e32 v78, v78, v79
	v_lshlrev_b32_e32 v104, 16, v80
	v_mul_f32_e32 v79, v101, v101
	v_fmac_f32_e32 v74, v96, v96
	v_fmac_f32_e32 v75, v94, v94
	v_and_b32_e32 v91, 0xffff0000, v76
	v_add_f32_e32 v86, v86, v90
	v_add_f32_e32 v82, v83, v82
	v_fmac_f32_e32 v79, v104, v104
	v_and_b32_e32 v97, 0xffff0000, v81
	v_add_f32_e32 v74, v74, v75
	v_lshlrev_b32_e32 v92, 16, v76
	v_mul_f32_e32 v75, v91, v91
	v_and_b32_e32 v87, 0xffff0000, v70
	v_and_b32_e32 v85, 0xffff0000, v71
	v_add_f32_e32 v82, v82, v86
	v_add_f32_e32 v78, v79, v78
	v_lshlrev_b32_e32 v102, 16, v81
	v_mul_f32_e32 v79, v97, v97
	v_fmac_f32_e32 v75, v92, v92
	v_and_b32_e32 v89, 0xffff0000, v77
	v_lshlrev_b32_e32 v88, 16, v70
	v_mul_f32_e32 v70, v87, v87
	v_lshlrev_b32_e32 v86, 16, v71
	v_mul_f32_e32 v71, v85, v85
	v_fmac_f32_e32 v79, v102, v102
	v_add_f32_e32 v74, v75, v74
	v_lshlrev_b32_e32 v90, 16, v77
	v_mul_f32_e32 v75, v89, v89
	v_fmac_f32_e32 v70, v88, v88
	v_fmac_f32_e32 v71, v86, v86
	v_lshlrev_b32_e32 v84, 16, v72
	v_and_b32_e32 v72, 0xffff0000, v72
	v_add_f32_e32 v78, v79, v78
	v_fmac_f32_e32 v75, v90, v90
	v_add_f32_e32 v70, v70, v71
	v_mul_f32_e32 v71, v72, v72
	v_add_f32_e32 v78, v78, v82
	v_add_f32_e32 v74, v75, v74
	v_fmac_f32_e32 v71, v84, v84
	v_add_f32_e32 v74, v74, v78
	v_add_f32_e32 v75, v71, v70
	v_and_b32_e32 v70, 0xffff0000, v73
	v_and_b32_e32 v80, 0xffff0000, v66
	v_and_b32_e32 v78, 0xffff0000, v67
	v_lshlrev_b32_e32 v71, 16, v73
	v_mul_f32_e32 v73, v70, v70
	v_lshlrev_b32_e32 v81, 16, v66
	v_mul_f32_e32 v66, v80, v80
	v_lshlrev_b32_e32 v79, 16, v67
	v_mul_f32_e32 v67, v78, v78
	v_fmac_f32_e32 v73, v71, v71
	v_fmac_f32_e32 v66, v81, v81
	v_fmac_f32_e32 v67, v79, v79
	v_and_b32_e32 v76, 0xffff0000, v68
	v_add_f32_e32 v73, v73, v75
	v_add_f32_e32 v66, v66, v67
	v_lshlrev_b32_e32 v77, 16, v68
	v_mul_f32_e32 v67, v76, v76
	v_add_f32_e32 v73, v73, v74
	v_fmac_f32_e32 v67, v77, v77
	v_and_b32_e32 v74, 0xffff0000, v69
	v_add_f32_e32 v66, v67, v66
	v_lshlrev_b32_e32 v75, 16, v69
	v_mul_f32_e32 v67, v74, v74
	v_fmac_f32_e32 v67, v75, v75
	v_add_f32_e32 v66, v67, v66
	v_add_f32_e32 v66, v66, v73
	ds_bpermute_b32 v67, v213, v66
	s_add_u32 s90, s6, s36
	s_addc_u32 s91, s7, s37
	v_lshlrev_b32_e32 v73, 2, v124
	v_or_b32_e32 v83, s88, v133
	s_waitcnt lgkmcnt(0)
	v_add_f32_e32 v66, v66, v67
	ds_bpermute_b32 v67, v214, v66
	v_mul_u32_u24_e32 v124, 0x110, v124
	v_lshlrev_b32_e32 v83, 1, v83
	v_add3_u32 v83, 0, v124, v83
	s_ashr_i32 s43, s42, 31
	s_waitcnt lgkmcnt(0)
; __device__ __forceinline__ unsigned pk2(float lo, float hi) { unsigned r; asm("v_cvt_pk_bf16_f32 %0, %1, %2" : "=v"(r) : "v"(lo), "v"(hi)); return r; }
; __device__ __forceinline__ float bf_lo(unsigned w) { return __uint_as_float(w << 16); }
; __device__ __forceinline__ float bf_hi(unsigned w) { return __uint_as_float(w & 0xffff0000u); }
; __device__ __forceinline__ void mixer_chunk(KP p, LAS unsigned char* lds, int l, int chunk) {
;     ...
;         const float* gg = p->gmlp_norm_g + l * 256 + 64 * q4;
; #pragma unroll
;         for (int i = 0; i < 8; ++i) {
;             const f32x4 g0 = *(const f32x4*)(gg + 8 * i), g1 = *(const f32x4*)(gg + 8 * i + 4);
; #pragma unroll
;             for (int e = 0; e < 4; ++e) { const int d = 8 * i + 2 * e; const float ga = e < 2 ? g0[2 * e] : g1[2 * e - 4], gb = e < 2 ? g0[2 * e + 1] : g1[2 * e - 3];
;                 const unsigned pk = pk2(bf_lo(vv[i][e]) * rs * ga, bf_hi(vv[i][e]) * rs * gb);
;                 VT[(64 * q4 + d) * VLD + j] = (bf16_t)(pk & 0xffff); VT[(64 * q4 + d + 1) * VLD + j] = (bf16_t)(pk >> 16); }
;         }
	v_add_f32_e32 v66, v66, v67
	v_fmamk_f32 v66, v66, 0x3b800000, v189
	v_rsq_f32_e32 v82, v66
	global_load_dwordx4 v[66:69], v73, s[90:91] offset:16
	global_load_dwordx4 v[134:137], v73, s[90:91]
	s_lshl_b64 s[6:7], s[42:43], 1
	s_lshl_b32 s18, s24, 1
	v_mul_f32_e32 v133, v82, v138
	v_mul_f32_e32 v124, v82, v140
	v_mul_f32_e32 v131, v82, v131
	v_mul_f32_e32 v128, v82, v128
	v_mul_f32_e32 v122, v82, v122
	v_mul_f32_e32 v119, v82, v119
	v_mul_f32_e32 v123, v82, v123
	v_mul_f32_e32 v121, v82, v121
	v_mul_f32_e32 v117, v82, v117
	v_mul_f32_e32 v114, v82, v114
	v_mul_f32_e32 v111, v82, v111
	v_mul_f32_e32 v115, v82, v115
	v_mul_f32_e32 v113, v82, v113
	v_mul_f32_e32 v109, v82, v109
	v_mul_f32_e32 v106, v82, v106
	v_mul_f32_e32 v103, v82, v103
	v_mul_f32_e32 v107, v82, v107
	v_mul_f32_e32 v105, v82, v105
	v_mul_f32_e32 v101, v82, v101
	v_mul_f32_e32 v95, v82, v95
	v_mul_f32_e32 v93, v82, v93
	v_mul_f32_e32 v92, v82, v92
	v_mul_f32_e32 v96, v82, v96
	v_mul_f32_e32 v94, v82, v94
	v_mul_f32_e32 v91, v82, v91
	v_mul_f32_e32 v87, v82, v87
	v_mul_f32_e32 v85, v82, v85
	v_mul_f32_e32 v84, v82, v84
	v_mul_f32_e32 v88, v82, v88
	v_mul_f32_e32 v86, v82, v86
	v_mul_f32_e32 v72, v82, v72
	v_mul_f32_e32 v81, v82, v81
	v_mul_f32_e32 v80, v82, v80
	s_mov_b32 s25, 0x8000
	v_mov_b32_e32 v187, v1
	s_waitcnt vmcnt(0)
	v_mul_f32_e32 v133, v134, v133
	v_mul_f32_e32 v134, v82, v139
	v_mul_f32_e32 v134, v135, v134
	v_cvt_pk_bf16_f32 v133, v133, v134
	ds_write_b16 v83, v133
	ds_write_b16_d16_hi v83, v133 offset:272
	v_mul_f32_e32 v124, v136, v124
	v_mul_f32_e32 v133, v82, v141
	v_mul_f32_e32 v133, v137, v133
	v_cvt_pk_bf16_f32 v124, v124, v133
	ds_write_b16 v83, v124 offset:544
	ds_write_b16_d16_hi v83, v124 offset:816
	v_mul_f32_e32 v124, v82, v142
	v_mul_f32_e32 v66, v66, v124
	v_mul_f32_e32 v124, v82, v143
	v_mul_f32_e32 v67, v67, v124
	v_cvt_pk_bf16_f32 v66, v66, v67
	ds_write_b16 v83, v66 offset:1088
	ds_write_b16_d16_hi v83, v66 offset:1360
	v_mul_f32_e32 v66, v82, v144
	v_mul_f32_e32 v66, v68, v66
	v_mul_f32_e32 v67, v82, v145
	v_mul_f32_e32 v67, v69, v67
	v_cvt_pk_bf16_f32 v66, v66, v67
	ds_write_b16 v83, v66 offset:1632
	ds_write_b16_d16_hi v83, v66 offset:1904
	global_load_dwordx4 v[66:69], v73, s[90:91] offset:48
	global_load_dwordx4 v[134:137], v73, s[90:91] offset:32
	v_mul_f32_e32 v124, v82, v132
	s_waitcnt vmcnt(0)
	v_mul_f32_e32 v124, v134, v124
	v_mul_f32_e32 v131, v135, v131
	v_cvt_pk_bf16_f32 v124, v124, v131
	ds_write_b16 v83, v124 offset:2176
	ds_write_b16_d16_hi v83, v124 offset:2448
	v_mul_f32_e32 v124, v82, v130
	v_mul_f32_e32 v124, v136, v124
	v_mul_f32_e32 v128, v137, v128
	v_cvt_pk_bf16_f32 v124, v124, v128
	ds_write_b16 v83, v124 offset:2720
	ds_write_b16_d16_hi v83, v124 offset:2992
	v_mul_f32_e32 v124, v82, v129
	v_mul_f32_e32 v66, v66, v124
	v_mul_f32_e32 v124, v82, v126
	v_mul_f32_e32 v67, v67, v124
	v_cvt_pk_bf16_f32 v66, v66, v67
	ds_write_b16 v83, v66 offset:3264
	ds_write_b16_d16_hi v83, v66 offset:3536
	v_mul_f32_e32 v66, v82, v127
	v_mul_f32_e32 v66, v68, v66
	v_mul_f32_e32 v67, v82, v125
	v_mul_f32_e32 v67, v69, v67
	v_cvt_pk_bf16_f32 v66, v66, v67
	ds_write_b16 v83, v66 offset:3808
	ds_write_b16_d16_hi v83, v66 offset:4080
	global_load_dwordx4 v[66:69], v73, s[90:91] offset:80
	global_load_dwordx4 v[124:127], v73, s[90:91] offset:64
	s_waitcnt vmcnt(1)
	v_mul_f32_e32 v67, v117, v67
	s_waitcnt vmcnt(0)
	v_mul_f32_e32 v122, v122, v125
	v_mul_f32_e32 v119, v119, v127
	v_mul_f32_e32 v123, v123, v124
	v_cvt_pk_bf16_f32 v122, v123, v122
	v_mul_f32_e32 v121, v121, v126
	v_cvt_pk_bf16_f32 v119, v121, v119
	ds_write_b16 v83, v122 offset:4352
	ds_write_b16_d16_hi v83, v122 offset:4624
	ds_write_b16 v83, v119 offset:4896
	ds_write_b16_d16_hi v83, v119 offset:5168
	v_mul_f32_e32 v119, v82, v120
	v_mul_f32_e32 v66, v119, v66
	v_cvt_pk_bf16_f32 v66, v66, v67
	ds_write_b16 v83, v66 offset:5440
	ds_write_b16_d16_hi v83, v66 offset:5712
	v_mul_f32_e32 v66, v82, v118
	v_mul_f32_e32 v66, v66, v68
	v_mul_f32_e32 v67, v82, v116
	v_mul_f32_e32 v67, v67, v69
	v_cvt_pk_bf16_f32 v66, v66, v67
	ds_write_b16 v83, v66 offset:5984
	ds_write_b16_d16_hi v83, v66 offset:6256
	global_load_dwordx4 v[66:69], v73, s[90:91] offset:112
	global_load_dwordx4 v[116:119], v73, s[90:91] offset:96
	s_waitcnt vmcnt(1)
	v_mul_f32_e32 v67, v109, v67
	s_waitcnt vmcnt(0)
	v_mul_f32_e32 v114, v114, v117
	v_mul_f32_e32 v111, v111, v119
	v_mul_f32_e32 v115, v115, v116
	v_cvt_pk_bf16_f32 v114, v115, v114
	v_mul_f32_e32 v113, v113, v118
	v_cvt_pk_bf16_f32 v111, v113, v111
	ds_write_b16 v83, v114 offset:6528
	ds_write_b16_d16_hi v83, v114 offset:6800
	ds_write_b16 v83, v111 offset:7072
	ds_write_b16_d16_hi v83, v111 offset:7344
	v_mul_f32_e32 v111, v82, v112
	v_mul_f32_e32 v66, v111, v66
	v_cvt_pk_bf16_f32 v66, v66, v67
	ds_write_b16 v83, v66 offset:7616
	ds_write_b16_d16_hi v83, v66 offset:7888
	v_mul_f32_e32 v66, v82, v110
	v_mul_f32_e32 v66, v66, v68
	v_mul_f32_e32 v67, v82, v108
	v_mul_f32_e32 v67, v67, v69
	v_cvt_pk_bf16_f32 v66, v66, v67
	ds_write_b16 v83, v66 offset:8160
	ds_write_b16_d16_hi v83, v66 offset:8432
	global_load_dwordx4 v[66:69], v73, s[90:91] offset:144
	global_load_dwordx4 v[108:111], v73, s[90:91] offset:128
	s_waitcnt vmcnt(1)
	v_mul_f32_e32 v67, v101, v67
	s_waitcnt vmcnt(0)
; #define LAS __attribute__((address_space(3)))
; __device__ __forceinline__ unsigned pk2(float lo, float hi) { unsigned r; asm("v_cvt_pk_bf16_f32 %0, %1, %2" : "=v"(r) : "v"(lo), "v"(hi)); return r; }
; __device__ __forceinline__ float bf_lo(unsigned w) { return __uint_as_float(w << 16); }
; __device__ __forceinline__ float bf_hi(unsigned w) { return __uint_as_float(w & 0xffff0000u); }
; __device__ __forceinline__ float rsq(float x) { return __builtin_amdgcn_rsqf(x); }
; template <int NNT>
; __device__ __forceinline__ void norm_store(const f32x4 (&acc)[8][NNT], const LAS float* part, bf16_t* dst, int fr) {
; #pragma unroll
;     for (int mt = 0; mt < 8; ++mt) {
;         const LAS f32x4* pp = (const LAS f32x4*)(part + (16 * mt + fr) * 8); const f32x4 a = pp[0], b = pp[1];
;         const float rs = rsq((((a[0] + a[1]) + (a[2] + a[3])) + ((b[0] + b[1]) + (b[2] + b[3]))) * (1.0f / 256.0f) + EPS);
; #pragma unroll
;         for (int nt = 0; nt < NNT; ++nt) { u32x2 o; o.x = pk2(acc[mt][nt][0] * rs, acc[mt][nt][1] * rs); o.y = pk2(acc[mt][nt][2] * rs, acc[mt][nt][3] * rs);
;             *(u32x2*)(dst + (size_t)(16 * mt) * DM + 16 * nt) = o; }
;     }
; }
; __device__ __forceinline__ void mixer_chunk(KP p, LAS unsigned char* lds, int l, int chunk) {
;     ...
;         const float* gg = p->gmlp_norm_g + l * 256 + 64 * q4;
; #pragma unroll
;         for (int i = 0; i < 8; ++i) {
;             const f32x4 g0 = *(const f32x4*)(gg + 8 * i), g1 = *(const f32x4*)(gg + 8 * i + 4);
; #pragma unroll
;             for (int e = 0; e < 4; ++e) { const int d = 8 * i + 2 * e; const float ga = e < 2 ? g0[2 * e] : g1[2 * e - 4], gb = e < 2 ? g0[2 * e + 1] : g1[2 * e - 3];
;                 const unsigned pk = pk2(bf_lo(vv[i][e]) * rs * ga, bf_hi(vv[i][e]) * rs * gb);
;                 VT[(64 * q4 + d) * VLD + j] = (bf16_t)(pk & 0xffff); VT[(64 * q4 + d + 1) * VLD + j] = (bf16_t)(pk >> 16); }
;         }
;     }
;     __syncthreads();
;     norm_store<2>(accp, part1, mrow + 512 + 64 * (w >> 1) + 32 * (w & 1), fr);
	v_mul_f32_e32 v106, v106, v109
	v_mul_f32_e32 v103, v103, v111
	v_mul_f32_e32 v107, v107, v108
	v_cvt_pk_bf16_f32 v106, v107, v106
	v_mul_f32_e32 v105, v105, v110
	v_cvt_pk_bf16_f32 v103, v105, v103
	ds_write_b16 v83, v106 offset:8704
	ds_write_b16_d16_hi v83, v106 offset:8976
	ds_write_b16 v83, v103 offset:9248
	ds_write_b16_d16_hi v83, v103 offset:9520
	v_mul_f32_e32 v103, v82, v104
	v_mul_f32_e32 v66, v103, v66
	v_cvt_pk_bf16_f32 v66, v66, v67
	ds_write_b16 v83, v66 offset:9792
	ds_write_b16_d16_hi v83, v66 offset:10064
	v_mul_f32_e32 v66, v82, v102
	v_mul_f32_e32 v66, v66, v68
	v_mul_f32_e32 v67, v82, v97
	v_mul_f32_e32 v67, v67, v69
	v_cvt_pk_bf16_f32 v66, v66, v67
	ds_write_b16 v83, v66 offset:10336
	ds_write_b16_d16_hi v83, v66 offset:10608
	global_load_dwordx4 v[66:69], v73, s[90:91] offset:176
	global_load_dwordx4 v[102:105], v73, s[90:91] offset:160
	s_waitcnt vmcnt(1)
	v_mul_f32_e32 v66, v92, v66
	s_waitcnt vmcnt(0)
	v_mul_f32_e32 v95, v95, v103
	v_mul_f32_e32 v93, v93, v105
	v_mul_f32_e32 v96, v96, v102
	v_cvt_pk_bf16_f32 v95, v96, v95
	v_mul_f32_e32 v94, v94, v104
	v_cvt_pk_bf16_f32 v93, v94, v93
	v_mul_f32_e32 v67, v91, v67
	v_cvt_pk_bf16_f32 v66, v66, v67
	ds_write_b16 v83, v95 offset:10880
	ds_write_b16_d16_hi v83, v95 offset:11152
	ds_write_b16 v83, v93 offset:11424
	ds_write_b16_d16_hi v83, v93 offset:11696
	ds_write_b16 v83, v66 offset:11968
	ds_write_b16_d16_hi v83, v66 offset:12240
	v_mul_f32_e32 v66, v82, v90
	v_mul_f32_e32 v66, v66, v68
	v_mul_f32_e32 v67, v82, v89
	v_mul_f32_e32 v67, v67, v69
	v_cvt_pk_bf16_f32 v66, v66, v67
	ds_write_b16 v83, v66 offset:12512
	ds_write_b16_d16_hi v83, v66 offset:12784
	global_load_dwordx4 v[66:69], v73, s[90:91] offset:208
	global_load_dwordx4 v[90:93], v73, s[90:91] offset:192
	s_waitcnt vmcnt(1)
	v_mul_f32_e32 v66, v84, v66
	s_waitcnt vmcnt(0)
	v_mul_f32_e32 v87, v87, v91
	v_mul_f32_e32 v85, v85, v93
	v_mul_f32_e32 v88, v88, v90
	v_cvt_pk_bf16_f32 v87, v88, v87
	v_mul_f32_e32 v86, v86, v92
	v_cvt_pk_bf16_f32 v85, v86, v85
	v_mul_f32_e32 v67, v72, v67
	v_cvt_pk_bf16_f32 v66, v66, v67
	ds_write_b16 v83, v87 offset:13056
	ds_write_b16_d16_hi v83, v87 offset:13328
	ds_write_b16 v83, v85 offset:13600
	ds_write_b16_d16_hi v83, v85 offset:13872
	ds_write_b16 v83, v66 offset:14144
	ds_write_b16_d16_hi v83, v66 offset:14416
	v_mul_f32_e32 v66, v82, v71
	v_mul_f32_e32 v66, v66, v68
	v_mul_f32_e32 v67, v82, v70
	v_mul_f32_e32 v67, v67, v69
	v_cvt_pk_bf16_f32 v66, v66, v67
	ds_write_b16 v83, v66 offset:14688
	ds_write_b16_d16_hi v83, v66 offset:14960
	global_load_dwordx4 v[66:69], v73, s[90:91] offset:240
	s_nop 0
	global_load_dwordx4 v[70:73], v73, s[90:91] offset:224
	s_waitcnt vmcnt(0)
	v_mul_f32_e32 v70, v81, v70
	v_mul_f32_e32 v71, v80, v71
	v_cvt_pk_bf16_f32 v70, v70, v71
	ds_write_b16 v83, v70 offset:15232
	ds_write_b16_d16_hi v83, v70 offset:15504
	v_mul_f32_e32 v70, v82, v79
	v_mul_f32_e32 v70, v70, v72
	v_mul_f32_e32 v71, v82, v78
	v_mul_f32_e32 v71, v71, v73
	v_cvt_pk_bf16_f32 v70, v70, v71
	ds_write_b16 v83, v70 offset:15776
	ds_write_b16_d16_hi v83, v70 offset:16048
	v_mul_f32_e32 v70, v82, v77
	v_mul_f32_e32 v66, v70, v66
	v_mul_f32_e32 v70, v82, v76
	v_mul_f32_e32 v67, v70, v67
	v_cvt_pk_bf16_f32 v66, v66, v67
	ds_write_b16 v83, v66 offset:16320
	ds_write_b16_d16_hi v83, v66 offset:16592
	v_mul_f32_e32 v66, v82, v75
	v_mul_f32_e32 v66, v66, v68
	v_mul_f32_e32 v67, v82, v74
	v_mul_f32_e32 v67, v67, v69
	v_cvt_pk_bf16_f32 v66, v66, v67
	ds_write_b16 v83, v66 offset:16864
	ds_write_b16_d16_hi v83, v66 offset:17136
	v_lshl_add_u64 v[66:67], v[170:171], 0, s[6:7]
	s_waitcnt lgkmcnt(0)
	s_barrier
	v_lshl_add_u64 v[82:83], v[66:67], 0, s[18:19]
	ds_read_b128 v[66:69], v99
	ds_read_b128 v[70:73], v99 offset:16
	v_add_co_u32_e32 v84, vcc, s25, v82
	s_mov_b32 s25, 0x18000
	s_waitcnt lgkmcnt(1)
	v_mov_b32_e32 v74, v66
	s_waitcnt lgkmcnt(0)
	v_mov_b32_e32 v75, v70
	v_mov_b32_e32 v70, v67
	v_pk_add_f32 v[66:67], v[74:75], v[70:71]
	v_mov_b32_e32 v70, v68
	v_mov_b32_e32 v71, v72
	v_mov_b32_e32 v72, v69
	v_pk_add_f32 v[68:69], v[70:71], v[72:73]
	v_addc_co_u32_e32 v85, vcc, 0, v83, vcc
	v_pk_add_f32 v[66:67], v[66:67], v[68:69]
	v_add_co_u32_e32 v86, vcc, s72, v82
	v_add_f32_e32 v66, v66, v67
	v_fmamk_f32 v66, v66, 0x3b800000, v189
	v_rsq_f32_e32 v66, v66
	v_addc_co_u32_e32 v87, vcc, 0, v83, vcc
	v_add_co_u32_e32 v88, vcc, s25, v82
	v_mul_f32_e32 v62, v62, v66
	v_mul_f32_e32 v63, v63, v66
	v_mul_f32_e32 v58, v58, v66
	v_mul_f32_e32 v59, v59, v66
	v_cvt_pk_bf16_f32 v62, v62, v63
	v_mul_f32_e32 v63, v64, v66
	v_cvt_pk_bf16_f32 v58, v58, v59
	v_mul_f32_e32 v59, v60, v66
	v_mul_f32_e32 v64, v65, v66
	v_cvt_pk_bf16_f32 v63, v63, v64
	s_nop 1
	v_mov_b32_e32 v244, v62
	v_mov_b32_e32 v245, v63
	v_mul_f32_e32 v60, v61, v66
	v_cvt_pk_bf16_f32 v59, v59, v60
	v_mov_b32_e32 v246, v58
	v_mov_b32_e32 v247, v59
	v_bfe_u32 v248, v193, 4, 1
	v_mul_u32_u24_e32 v248, 24, v248
	v_add_co_u32_e64 v248, s[98:99], v248, v82
	s_nop 1
	v_addc_co_u32_e64 v249, s[98:99], 0, v83, s[98:99]
	v_permlane16_swap_b32_e32 v244, v246
	v_permlane16_swap_b32_e32 v245, v247
	global_store_dwordx4 v[248:249], v[244:247], off offset:1024
	ds_read_b128 v[58:61], v99 offset:512
	ds_read_b128 v[62:65], v99 offset:528
	v_addc_co_u32_e32 v89, vcc, 0, v83, vcc
	s_mov_b32 s25, 0x20000
	s_waitcnt lgkmcnt(1)
	v_mov_b32_e32 v66, v58
	s_waitcnt lgkmcnt(0)
; #define LAS __attribute__((address_space(3)))
; __device__ __forceinline__ unsigned pk2(float lo, float hi) { unsigned r; asm("v_cvt_pk_bf16_f32 %0, %1, %2" : "=v"(r) : "v"(lo), "v"(hi)); return r; }
; __device__ __forceinline__ float rsq(float x) { return __builtin_amdgcn_rsqf(x); }
; template <int NNT>
; __device__ __forceinline__ void norm_store(const f32x4 (&acc)[8][NNT], const LAS float* part, bf16_t* dst, int fr) {
; #pragma unroll
;     for (int mt = 0; mt < 8; ++mt) {
;         const LAS f32x4* pp = (const LAS f32x4*)(part + (16 * mt + fr) * 8); const f32x4 a = pp[0], b = pp[1];
;         const float rs = rsq((((a[0] + a[1]) + (a[2] + a[3])) + ((b[0] + b[1]) + (b[2] + b[3]))) * (1.0f / 256.0f) + EPS);
; #pragma unroll
;         for (int nt = 0; nt < NNT; ++nt) { u32x2 o; o.x = pk2(acc[mt][nt][0] * rs, acc[mt][nt][1] * rs); o.y = pk2(acc[mt][nt][2] * rs, acc[mt][nt][3] * rs);
;             *(u32x2*)(dst + (size_t)(16 * mt) * DM + 16 * nt) = o; }
;     }
; }
	v_mov_b32_e32 v67, v62
	v_mov_b32_e32 v62, v59
	v_pk_add_f32 v[58:59], v[66:67], v[62:63]
	v_mov_b32_e32 v62, v60
	v_mov_b32_e32 v63, v64
	v_mov_b32_e32 v64, v61
	v_pk_add_f32 v[60:61], v[62:63], v[64:65]
	v_add_co_u32_e32 v90, vcc, s25, v82
	v_pk_add_f32 v[58:59], v[58:59], v[60:61]
	s_nop 0
	v_addc_co_u32_e32 v91, vcc, 0, v83, vcc
	v_add_f32_e32 v58, v58, v59
	v_fmamk_f32 v58, v58, 0x3b800000, v189
	v_rsq_f32_e32 v58, v58
	s_mov_b32 s25, 0x28000
	v_add_co_u32_e32 v92, vcc, s25, v82
	v_mul_f32_e32 v54, v54, v58
	v_mul_f32_e32 v55, v55, v58
	v_mul_f32_e32 v50, v50, v58
	v_mul_f32_e32 v51, v51, v58
	v_cvt_pk_bf16_f32 v54, v54, v55
	v_mul_f32_e32 v55, v56, v58
	v_cvt_pk_bf16_f32 v50, v50, v51
	v_mul_f32_e32 v51, v52, v58
	v_mul_f32_e32 v56, v57, v58
	v_cvt_pk_bf16_f32 v55, v55, v56
	s_nop 1
	v_mov_b32_e32 v244, v54
	v_mov_b32_e32 v245, v55
	v_mul_f32_e32 v52, v53, v58
	v_cvt_pk_bf16_f32 v51, v51, v52
	v_mov_b32_e32 v246, v50
	v_mov_b32_e32 v247, v51
	v_bfe_u32 v248, v193, 4, 1
	v_mul_u32_u24_e32 v248, 24, v248
	v_add_co_u32_e64 v248, s[98:99], v248, v84
	s_nop 1
	v_addc_co_u32_e64 v249, s[98:99], 0, v85, s[98:99]
	v_permlane16_swap_b32_e32 v244, v246
	v_permlane16_swap_b32_e32 v245, v247
	global_store_dwordx4 v[248:249], v[244:247], off offset:1024
	ds_read_b128 v[50:53], v99 offset:1024
	ds_read_b128 v[54:57], v99 offset:1040
	v_addc_co_u32_e32 v93, vcc, 0, v83, vcc
	s_mov_b32 s25, 0x30000
	s_waitcnt lgkmcnt(1)
	v_mov_b32_e32 v58, v50
	s_waitcnt lgkmcnt(0)
	v_mov_b32_e32 v59, v54
	v_mov_b32_e32 v54, v51
	v_pk_add_f32 v[50:51], v[58:59], v[54:55]
	v_mov_b32_e32 v54, v52
	v_mov_b32_e32 v55, v56
	v_mov_b32_e32 v56, v53
	v_pk_add_f32 v[52:53], v[54:55], v[56:57]
	v_add_co_u32_e32 v94, vcc, s25, v82
	v_pk_add_f32 v[50:51], v[50:51], v[52:53]
	s_nop 0
	v_addc_co_u32_e32 v95, vcc, 0, v83, vcc
	v_add_f32_e32 v50, v50, v51
	v_fmamk_f32 v50, v50, 0x3b800000, v189
	v_rsq_f32_e32 v50, v50
	s_mov_b32 s25, 0x38000
	v_add_co_u32_e32 v96, vcc, s25, v82
	v_mul_f32_e32 v46, v46, v50
	v_mul_f32_e32 v47, v47, v50
	v_mul_f32_e32 v42, v42, v50
	v_mul_f32_e32 v43, v43, v50
	v_cvt_pk_bf16_f32 v46, v46, v47
	v_mul_f32_e32 v47, v48, v50
	v_cvt_pk_bf16_f32 v42, v42, v43
	v_mul_f32_e32 v43, v44, v50
	v_mul_f32_e32 v48, v49, v50
	v_cvt_pk_bf16_f32 v47, v47, v48
	s_nop 1
	v_mov_b32_e32 v244, v46
	v_mov_b32_e32 v245, v47
	v_mul_f32_e32 v44, v45, v50
	v_cvt_pk_bf16_f32 v43, v43, v44
	v_mov_b32_e32 v246, v42
	v_mov_b32_e32 v247, v43
	v_bfe_u32 v248, v193, 4, 1
	v_mul_u32_u24_e32 v248, 24, v248
	v_add_co_u32_e64 v248, s[98:99], v248, v86
	s_nop 1
	v_addc_co_u32_e64 v249, s[98:99], 0, v87, s[98:99]
	v_permlane16_swap_b32_e32 v244, v246
	v_permlane16_swap_b32_e32 v245, v247
	global_store_dwordx4 v[248:249], v[244:247], off offset:1024
	ds_read_b128 v[42:45], v99 offset:1536
	ds_read_b128 v[46:49], v99 offset:1552
	v_addc_co_u32_e32 v97, vcc, 0, v83, vcc
	s_waitcnt lgkmcnt(1)
	v_mov_b32_e32 v50, v42
	s_waitcnt lgkmcnt(0)
	v_mov_b32_e32 v51, v46
	v_mov_b32_e32 v46, v43
	v_pk_add_f32 v[42:43], v[50:51], v[46:47]
	v_mov_b32_e32 v46, v44
	v_mov_b32_e32 v47, v48
	v_mov_b32_e32 v48, v45
	v_pk_add_f32 v[44:45], v[46:47], v[48:49]
	s_nop 0
	v_pk_add_f32 v[42:43], v[42:43], v[44:45]
	s_nop 0
	v_add_f32_e32 v42, v42, v43
	v_fmamk_f32 v42, v42, 0x3b800000, v189
	v_rsq_f32_e32 v42, v42
	s_nop 0
	v_mul_f32_e32 v38, v38, v42
	v_mul_f32_e32 v39, v39, v42
	v_mul_f32_e32 v34, v34, v42
	v_mul_f32_e32 v35, v35, v42
	v_cvt_pk_bf16_f32 v38, v38, v39
	v_mul_f32_e32 v39, v40, v42
	v_cvt_pk_bf16_f32 v34, v34, v35
	v_mul_f32_e32 v35, v36, v42
	v_mul_f32_e32 v40, v41, v42
	v_cvt_pk_bf16_f32 v39, v39, v40
	s_nop 1
	v_mov_b32_e32 v244, v38
	v_mov_b32_e32 v245, v39
	v_mul_f32_e32 v36, v37, v42
	v_cvt_pk_bf16_f32 v35, v35, v36
	v_mov_b32_e32 v246, v34
	v_mov_b32_e32 v247, v35
	v_bfe_u32 v248, v193, 4, 1
	v_mul_u32_u24_e32 v248, 24, v248
	v_add_co_u32_e64 v248, s[98:99], v248, v88
	s_nop 1
	v_addc_co_u32_e64 v249, s[98:99], 0, v89, s[98:99]
	v_permlane16_swap_b32_e32 v244, v246
	v_permlane16_swap_b32_e32 v245, v247
	global_store_dwordx4 v[248:249], v[244:247], off offset:1024
	ds_read_b128 v[34:37], v99 offset:2048
	ds_read_b128 v[38:41], v99 offset:2064
	s_waitcnt lgkmcnt(1)
	v_mov_b32_e32 v42, v34
	s_waitcnt lgkmcnt(0)
	v_mov_b32_e32 v43, v38
	v_mov_b32_e32 v38, v35
	v_pk_add_f32 v[34:35], v[42:43], v[38:39]
	v_mov_b32_e32 v38, v36
	v_mov_b32_e32 v39, v40
	v_mov_b32_e32 v40, v37
	v_pk_add_f32 v[36:37], v[38:39], v[40:41]
	v_mov_b64_e32 v[38:39], s[44:45]
	v_pk_add_f32 v[34:35], v[34:35], v[36:37]
	s_nop 0
	v_add_f32_e32 v34, v34, v35
	v_fmamk_f32 v34, v34, 0x3b800000, v189
	v_rsq_f32_e32 v34, v34
	s_nop 0
	v_mul_f32_e32 v30, v30, v34
	v_mul_f32_e32 v31, v31, v34
	v_mul_f32_e32 v26, v26, v34
	v_mul_f32_e32 v27, v27, v34
	v_cvt_pk_bf16_f32 v30, v30, v31
	v_mul_f32_e32 v31, v32, v34
	v_cvt_pk_bf16_f32 v26, v26, v27
	v_mul_f32_e32 v27, v28, v34
	v_mul_f32_e32 v32, v33, v34
	v_cvt_pk_bf16_f32 v31, v31, v32
	s_nop 1
	v_mov_b32_e32 v244, v30
	v_mov_b32_e32 v245, v31
	v_mul_f32_e32 v28, v29, v34
	v_cvt_pk_bf16_f32 v27, v27, v28
	v_mov_b32_e32 v246, v26
	v_mov_b32_e32 v247, v27
	v_bfe_u32 v248, v193, 4, 1
	v_mul_u32_u24_e32 v248, 24, v248
	v_add_co_u32_e64 v248, s[98:99], v248, v90
	s_nop 1
	v_addc_co_u32_e64 v249, s[98:99], 0, v91, s[98:99]
	v_permlane16_swap_b32_e32 v244, v246
	v_permlane16_swap_b32_e32 v245, v247
	global_store_dwordx4 v[248:249], v[244:247], off offset:1024
	ds_read_b128 v[26:29], v99 offset:2560
	ds_read_b128 v[30:33], v99 offset:2576
	s_waitcnt lgkmcnt(1)
	v_mov_b32_e32 v34, v26
	s_waitcnt lgkmcnt(0)
; #define LAS __attribute__((address_space(3)))
; __device__ __forceinline__ unsigned pk2(float lo, float hi) { unsigned r; asm("v_cvt_pk_bf16_f32 %0, %1, %2" : "=v"(r) : "v"(lo), "v"(hi)); return r; }
; __device__ __forceinline__ float rsq(float x) { return __builtin_amdgcn_rsqf(x); }
; template <int NNT>
; __device__ __forceinline__ void norm_store(const f32x4 (&acc)[8][NNT], const LAS float* part, bf16_t* dst, int fr) {
; #pragma unroll
;     for (int mt = 0; mt < 8; ++mt) {
;         const LAS f32x4* pp = (const LAS f32x4*)(part + (16 * mt + fr) * 8); const f32x4 a = pp[0], b = pp[1];
;         const float rs = rsq((((a[0] + a[1]) + (a[2] + a[3])) + ((b[0] + b[1]) + (b[2] + b[3]))) * (1.0f / 256.0f) + EPS);
; #pragma unroll
;         for (int nt = 0; nt < NNT; ++nt) { u32x2 o; o.x = pk2(acc[mt][nt][0] * rs, acc[mt][nt][1] * rs); o.y = pk2(acc[mt][nt][2] * rs, acc[mt][nt][3] * rs);
;             *(u32x2*)(dst + (size_t)(16 * mt) * DM + 16 * nt) = o; }
;     }
; }
; __device__ __forceinline__ void mixer_chunk(KP p, LAS unsigned char* lds, int l, int chunk) {
;     ...
;     {
;         const int h = w >> 1, t0 = 2 * (w & 1);
;         bf16x8 vf[2][4];
; #pragma unroll
;         for (int n = 0; n < 2; ++n)
; #pragma unroll
;             for (int ks = 0; ks < 4; ++ks) vf[n][ks] = *(const LAS bf16x8*)(VT + (64 * h + 16 * (t0 + n) + fr) * VLD + 32 * ks + 8 * fq);
;         const bf16_t* gwp = (const bf16_t*)(ws + OFF_GWS + l * SZ_GWS) + (size_t)(h * 128 + fr) * 128 + 8 * fq;
;         u32x2 uu[16]; float bias[8];
; #pragma unroll
;         for (int mt = 0; mt < 8; ++mt) {
;             bias[mt] = p->gmlp_bs[(l * 4 + h) * 128 + 16 * mt + fr];
; #pragma unroll
;             for (int n = 0; n < 2; ++n) uu[2 * mt + n] = *(const u32x2*)(zb + (size_t)(c0 + 16 * mt + fr) * DIN_P + ZC_U + 64 * h + 16 * (t0 + n) + 4 * fq);
;         }
	v_mov_b32_e32 v35, v30
	v_mov_b32_e32 v30, v27
	v_pk_add_f32 v[26:27], v[34:35], v[30:31]
	v_mov_b32_e32 v30, v28
	v_mov_b32_e32 v31, v32
	v_mov_b32_e32 v32, v29
	v_pk_add_f32 v[28:29], v[30:31], v[32:33]
	s_nop 0
	v_pk_add_f32 v[26:27], v[26:27], v[28:29]
	s_nop 0
	v_add_f32_e32 v26, v26, v27
	v_fmamk_f32 v26, v26, 0x3b800000, v189
	v_rsq_f32_e32 v26, v26
	s_nop 0
	v_mul_f32_e32 v22, v22, v26
	v_mul_f32_e32 v23, v23, v26
	v_mul_f32_e32 v18, v18, v26
	v_mul_f32_e32 v19, v19, v26
	v_cvt_pk_bf16_f32 v22, v22, v23
	v_mul_f32_e32 v23, v24, v26
	v_cvt_pk_bf16_f32 v18, v18, v19
	v_mul_f32_e32 v19, v20, v26
	v_mul_f32_e32 v24, v25, v26
	v_cvt_pk_bf16_f32 v23, v23, v24
	s_nop 1
	v_mov_b32_e32 v244, v22
	v_mov_b32_e32 v245, v23
	v_mul_f32_e32 v20, v21, v26
	v_cvt_pk_bf16_f32 v19, v19, v20
	v_mov_b32_e32 v246, v18
	v_mov_b32_e32 v247, v19
	v_bfe_u32 v248, v193, 4, 1
	v_mul_u32_u24_e32 v248, 24, v248
	v_add_co_u32_e64 v248, s[98:99], v248, v92
	s_nop 1
	v_addc_co_u32_e64 v249, s[98:99], 0, v93, s[98:99]
	v_permlane16_swap_b32_e32 v244, v246
	v_permlane16_swap_b32_e32 v245, v247
	global_store_dwordx4 v[248:249], v[244:247], off offset:1024
	ds_read_b128 v[18:21], v99 offset:3072
	ds_read_b128 v[22:25], v99 offset:3088
	s_waitcnt lgkmcnt(1)
	v_mov_b32_e32 v26, v18
	s_waitcnt lgkmcnt(0)
	v_mov_b32_e32 v27, v22
	v_mov_b32_e32 v22, v19
	v_pk_add_f32 v[18:19], v[26:27], v[22:23]
	v_mov_b32_e32 v22, v20
	v_mov_b32_e32 v23, v24
	v_mov_b32_e32 v24, v21
	v_pk_add_f32 v[20:21], v[22:23], v[24:25]
	s_nop 0
	v_pk_add_f32 v[18:19], v[18:19], v[20:21]
	s_nop 0
	v_add_f32_e32 v18, v18, v19
	v_fmamk_f32 v18, v18, 0x3b800000, v189
	v_rsq_f32_e32 v18, v18
	s_nop 0
	v_mul_f32_e32 v14, v14, v18
	v_mul_f32_e32 v15, v15, v18
	v_mul_f32_e32 v10, v10, v18
	v_mul_f32_e32 v11, v11, v18
	v_cvt_pk_bf16_f32 v14, v14, v15
	v_mul_f32_e32 v15, v16, v18
	v_cvt_pk_bf16_f32 v10, v10, v11
	v_mul_f32_e32 v11, v12, v18
	v_mul_f32_e32 v16, v17, v18
	v_cvt_pk_bf16_f32 v15, v15, v16
	s_nop 1
	v_mov_b32_e32 v244, v14
	v_mov_b32_e32 v245, v15
	v_mul_f32_e32 v12, v13, v18
	v_cvt_pk_bf16_f32 v11, v11, v12
	v_mov_b32_e32 v246, v10
	v_mov_b32_e32 v247, v11
	v_bfe_u32 v248, v193, 4, 1
	v_mul_u32_u24_e32 v248, 24, v248
	v_add_co_u32_e64 v248, s[98:99], v248, v94
	s_nop 1
	v_addc_co_u32_e64 v249, s[98:99], 0, v95, s[98:99]
	v_permlane16_swap_b32_e32 v244, v246
	v_permlane16_swap_b32_e32 v245, v247
	global_store_dwordx4 v[248:249], v[244:247], off offset:1024
	ds_read_b128 v[10:13], v99 offset:3584
	ds_read_b128 v[14:17], v99 offset:3600
	s_waitcnt lgkmcnt(1)
	v_mov_b32_e32 v18, v10
	s_waitcnt lgkmcnt(0)
	v_mov_b32_e32 v19, v14
	v_mov_b32_e32 v14, v11
	v_pk_add_f32 v[10:11], v[18:19], v[14:15]
	v_mov_b32_e32 v14, v12
	v_mov_b32_e32 v15, v16
	v_mov_b32_e32 v16, v13
	v_pk_add_f32 v[12:13], v[14:15], v[16:17]
	s_nop 0
	v_pk_add_f32 v[10:11], v[10:11], v[12:13]
	s_nop 0
	v_add_f32_e32 v10, v10, v11
	v_fmamk_f32 v10, v10, 0x3b800000, v189
	v_rsq_f32_e32 v10, v10
	s_nop 0
	v_mul_f32_e32 v2, v2, v10
	v_mul_f32_e32 v3, v3, v10
	v_cvt_pk_bf16_f32 v2, v2, v3
	v_mul_f32_e32 v3, v4, v10
	v_mul_f32_e32 v4, v5, v10
	v_cvt_pk_bf16_f32 v3, v3, v4
	s_nop 1
	v_mov_b32_e32 v244, v2
	v_mov_b32_e32 v245, v3
	v_mul_f32_e32 v2, v6, v10
	v_mul_f32_e32 v3, v7, v10
	v_cvt_pk_bf16_f32 v2, v2, v3
	v_mul_f32_e32 v3, v8, v10
	v_mul_f32_e32 v4, v9, v10
	v_cvt_pk_bf16_f32 v3, v3, v4
	v_mov_b32_e32 v246, v2
	v_mov_b32_e32 v247, v3
	v_bfe_u32 v248, v193, 4, 1
	v_mul_u32_u24_e32 v248, 24, v248
	v_add_co_u32_e64 v248, s[98:99], v248, v96
	s_nop 1
	v_addc_co_u32_e64 v249, s[98:99], 0, v97, s[98:99]
	v_permlane16_swap_b32_e32 v244, v246
	v_permlane16_swap_b32_e32 v245, v247
	global_store_dwordx4 v[248:249], v[244:247], off offset:1024
	v_add_u32_e32 v2, 0, v0
	v_mad_u64_u32 v[4:5], s[42:43], v98, s64, v[2:3]
	v_add_u32_e32 v3, s24, v100
	v_mad_u64_u32 v[10:11], s[24:25], v3, s64, v[2:3]
	s_and_b32 s24, s54, 0xffffff80
	v_readlane_b32 s25, v252, 4
	v_or_b32_e32 v34, s24, v217
	s_add_i32 s24, s24, s25
	v_or_b32_e32 v36, s24, v217
	v_mad_i64_i32 v[40:41], s[24:25], v168, s65, v[38:39]
	v_lshl_add_u64 v[40:41], v[40:41], 0, s[6:7]
	v_ashrrev_i32_e32 v37, 31, v36
	v_lshl_add_u64 v[40:41], v[40:41], 0, v[186:187]
	v_lshl_add_u64 v[36:37], v[36:37], 2, s[96:97]
	v_lshl_add_u64 v[40:41], v[40:41], 0, s[18:19]
	ds_read_b128 v[30:33], v4
	ds_read_b128 v[26:29], v4 offset:64
	ds_read_b128 v[22:25], v4 offset:128
	ds_read_b128 v[18:21], v4 offset:192
	ds_read_b128 v[14:17], v10 offset:4352
	ds_read_b128 v[2:5], v10 offset:4416
	ds_read_b128 v[6:9], v10 offset:4480
	ds_read_b128 v[10:13], v10 offset:4544
	global_load_dword v48, v[36:37], off
	global_load_dwordx2 v[44:45], v[40:41], off offset:2240
	global_load_dwordx2 v[42:43], v[40:41], off offset:2272
	global_load_dword v134, v[36:37], off offset:64
	v_mad_i64_i32 v[40:41], s[24:25], v184, s65, v[38:39]
	v_lshl_add_u64 v[40:41], v[40:41], 0, s[6:7]
	v_lshl_add_u64 v[40:41], v[40:41], 0, v[186:187]
	v_lshl_add_u64 v[40:41], v[40:41], 0, s[18:19]
	global_load_dwordx2 v[124:125], v[40:41], off offset:2240
	global_load_dwordx2 v[122:123], v[40:41], off offset:2272
	global_load_dword v133, v[36:37], off offset:128
	v_mad_i64_i32 v[40:41], s[24:25], v182, s65, v[38:39]
	v_lshl_add_u64 v[40:41], v[40:41], 0, s[6:7]
	v_lshl_add_u64 v[40:41], v[40:41], 0, v[186:187]
	v_lshl_add_u64 v[40:41], v[40:41], 0, s[18:19]
	global_load_dwordx2 v[120:121], v[40:41], off offset:2240
	global_load_dwordx2 v[118:119], v[40:41], off offset:2272
	global_load_dword v132, v[36:37], off offset:192
	v_mad_i64_i32 v[40:41], s[24:25], v180, s65, v[38:39]
	v_lshl_add_u64 v[40:41], v[40:41], 0, s[6:7]
; __device__ __forceinline__ float bf_lo(unsigned w) { return __uint_as_float(w << 16); }
; __device__ __forceinline__ float bf_hi(unsigned w) { return __uint_as_float(w & 0xffff0000u); }
; __device__ __forceinline__ f32x4 mfma16(bf16x8 a, bf16x8 b, f32x4 c) { return __builtin_amdgcn_mfma_f32_16x16x32_bf16(a, b, c, 0, 0, 0); }
; __device__ __forceinline__ void mixer_chunk(KP p, LAS unsigned char* lds, int l, int chunk) {
;     ...
;         const bf16_t* gwp = (const bf16_t*)(ws + OFF_GWS + l * SZ_GWS) + (size_t)(h * 128 + fr) * 128 + 8 * fq;
;         u32x2 uu[16]; float bias[8];
; #pragma unroll
;         for (int mt = 0; mt < 8; ++mt) {
;             bias[mt] = p->gmlp_bs[(l * 4 + h) * 128 + 16 * mt + fr];
; #pragma unroll
;             for (int n = 0; n < 2; ++n) uu[2 * mt + n] = *(const u32x2*)(zb + (size_t)(c0 + 16 * mt + fr) * DIN_P + ZC_U + 64 * h + 16 * (t0 + n) + 4 * fq);
;         }
;         f32x4 acc[8][2];
; #pragma unroll
;         for (int mp = 0; mp < 4; ++mp) {
;             u32x4 wf[8];
; #pragma unroll
;             for (int q = 0; q < 2; ++q)
; #pragma unroll
;                 for (int ks = 0; ks < 4; ++ks) wf[4 * q + ks] = *(const u32x4*)(gwp + (size_t)(16 * (2 * mp + q)) * 128 + 32 * (ks <= mp ? ks : 0));
;             pin(wf);
; #pragma unroll
;             for (int q = 0; q < 2; ++q)
; #pragma unroll
;                 for (int n = 0; n < 2; ++n) { f32x4 a = (f32x4){0.f, 0.f, 0.f, 0.f};
; #pragma unroll
;                     for (int ks = 0; ks < 4; ++ks) if (ks <= mp) a = mfma16(vf[n][ks], as_bf16x8(wf[4 * q + ks]), a);
;                     const int mt = 2 * mp + q; const u32x2 u2 = uu[2 * mt + n]; const float bs_ = bias[mt];
;                     a[0] = bf_lo(u2.x) * (a[0] + bs_); a[1] = bf_hi(u2.x) * (a[1] + bs_); a[2] = bf_lo(u2.y) * (a[2] + bs_); a[3] = bf_hi(u2.y) * (a[3] + bs_);
;                     acc[mt][n] = a; }
	v_lshl_add_u64 v[40:41], v[40:41], 0, v[186:187]
	v_lshl_add_u64 v[40:41], v[40:41], 0, s[18:19]
	global_load_dwordx2 v[116:117], v[40:41], off offset:2240
	global_load_dwordx2 v[114:115], v[40:41], off offset:2272
	global_load_dword v131, v[36:37], off offset:256
	v_mad_i64_i32 v[40:41], s[24:25], v178, s65, v[38:39]
	v_lshl_add_u64 v[40:41], v[40:41], 0, s[6:7]
	v_lshl_add_u64 v[40:41], v[40:41], 0, v[186:187]
	v_lshl_add_u64 v[40:41], v[40:41], 0, s[18:19]
	global_load_dwordx2 v[112:113], v[40:41], off offset:2240
	global_load_dwordx2 v[110:111], v[40:41], off offset:2272
	global_load_dword v130, v[36:37], off offset:320
	v_mad_i64_i32 v[40:41], s[24:25], v176, s65, v[38:39]
	v_lshl_add_u64 v[40:41], v[40:41], 0, s[6:7]
	v_lshl_add_u64 v[40:41], v[40:41], 0, v[186:187]
	v_lshl_add_u64 v[40:41], v[40:41], 0, s[18:19]
	global_load_dwordx2 v[108:109], v[40:41], off offset:2240
	global_load_dwordx2 v[106:107], v[40:41], off offset:2272
	global_load_dword v129, v[36:37], off offset:384
	v_mad_i64_i32 v[40:41], s[24:25], v174, s65, v[38:39]
	v_lshl_add_u64 v[40:41], v[40:41], 0, s[6:7]
	v_ashrrev_i32_e32 v35, 31, v34
	v_lshl_add_u64 v[40:41], v[40:41], 0, v[186:187]
	v_lshlrev_b64 v[34:35], 8, v[34:35]
	v_lshl_add_u64 v[40:41], v[40:41], 0, s[18:19]
	v_lshl_add_u64 v[34:35], s[48:49], 0, v[34:35]
	global_load_dwordx2 v[104:105], v[40:41], off offset:2240
	global_load_dwordx2 v[102:103], v[40:41], off offset:2272
	global_load_dword v128, v[36:37], off offset:448
	v_mad_i64_i32 v[36:37], s[24:25], v172, s65, v[38:39]
	v_lshl_add_u64 v[36:37], v[36:37], 0, s[6:7]
	v_lshl_add_u64 v[126:127], v[34:35], 0, v[0:1]
	v_lshl_add_u64 v[36:37], v[36:37], 0, v[186:187]
	v_add_co_u32_e32 v46, vcc, s39, v126
	v_lshl_add_u64 v[36:37], v[36:37], 0, s[18:19]
	s_nop 0
	v_addc_co_u32_e32 v47, vcc, 0, v127, vcc
	global_load_dwordx2 v[100:101], v[36:37], off offset:2240
	global_load_dwordx2 v[98:99], v[36:37], off offset:2272
	global_load_dwordx4 v[38:41], v[126:127], off
	s_movk_i32 s6, 0x4000
	global_load_dwordx4 v[34:37], v[46:47], off offset:-4096
	s_waitcnt vmcnt(24)
	v_lshlrev_b32_e32 v0, 16, v44
	s_waitcnt vmcnt(1)
	v_mov_b64_e32 v[60:61], v[40:41]
	v_mov_b64_e32 v[64:65], v[40:41]
	s_waitcnt vmcnt(0)
	v_mov_b64_e32 v[52:53], v[36:37]
	v_mov_b64_e32 v[56:57], v[36:37]
	v_mov_b64_e32 v[68:69], v[40:41]
	v_mov_b64_e32 v[72:73], v[36:37]
	v_mov_b64_e32 v[50:51], v[34:35]
	v_mov_b64_e32 v[54:55], v[34:35]
	v_mov_b64_e32 v[58:59], v[38:39]
	v_mov_b64_e32 v[62:63], v[38:39]
	v_mov_b64_e32 v[66:67], v[38:39]
	v_mov_b64_e32 v[70:71], v[34:35]
	s_waitcnt lgkmcnt(7)
	v_mfma_f32_16x16x32_bf16 v[38:41], v[30:33], v[58:61], 0
	v_mfma_f32_16x16x32_bf16 v[74:77], v[30:33], v[34:37], 0
	s_waitcnt lgkmcnt(3)
	v_mfma_f32_16x16x32_bf16 v[66:69], v[14:17], v[34:37], 0
	s_nop 4
	v_add_f32_e32 v38, v48, v38
	v_mul_f32_e32 v0, v38, v0
	v_and_b32_e32 v38, 0xffff0000, v44
	v_add_f32_e32 v39, v48, v39
	v_mul_f32_e32 v135, v39, v38
	v_lshlrev_b32_e32 v38, 16, v45
	v_add_f32_e32 v39, v48, v40
	v_mul_f32_e32 v136, v39, v38
	v_and_b32_e32 v38, 0xffff0000, v45
	v_add_f32_e32 v39, v48, v41
	v_mul_f32_e32 v137, v39, v38
	v_mfma_f32_16x16x32_bf16 v[38:41], v[14:17], v[58:61], 0
	v_lshlrev_b32_e32 v44, 16, v42
	s_nop 6
	v_add_f32_e32 v38, v48, v38
	v_mul_f32_e32 v138, v38, v44
	v_and_b32_e32 v38, 0xffff0000, v42
	v_add_f32_e32 v39, v48, v39
	v_mul_f32_e32 v139, v39, v38
	v_lshlrev_b32_e32 v38, 16, v43
	v_add_f32_e32 v39, v48, v40
	v_mul_f32_e32 v140, v39, v38
	v_and_b32_e32 v38, 0xffff0000, v43
	v_add_f32_e32 v39, v48, v41
	v_mul_f32_e32 v141, v39, v38
	global_load_dwordx4 v[34:37], v[46:47], off
	global_load_dwordx4 v[38:41], v[46:47], off offset:64
	v_add_co_u32_e32 v46, vcc, s68, v126
	s_waitcnt vmcnt(1)
	v_mov_b64_e32 v[52:53], v[36:37]
	v_addc_co_u32_e32 v47, vcc, 0, v127, vcc
	v_add_co_u32_e32 v142, vcc, s6, v126
	v_mov_b64_e32 v[56:57], v[36:37]
	s_nop 0
	v_addc_co_u32_e32 v143, vcc, 0, v127, vcc
	global_load_dwordx4 v[42:45], v[142:143], off offset:-4096
	s_nop 0
	global_load_dwordx4 v[46:49], v[46:47], off offset:64
	v_mov_b64_e32 v[50:51], v[34:35]
	v_mov_b64_e32 v[54:55], v[34:35]
	s_movk_i32 s6, 0x5000
	s_waitcnt vmcnt(1)
	v_mov_b64_e32 v[60:61], v[44:45]
	v_mov_b64_e32 v[64:65], v[44:45]
	v_mov_b64_e32 v[58:59], v[42:43]
	v_mov_b64_e32 v[62:63], v[42:43]
	s_waitcnt vmcnt(0)
; #define LAS __attribute__((address_space(3)))
; __device__ __forceinline__ float bf_lo(unsigned w) { return __uint_as_float(w << 16); }
; __device__ __forceinline__ float bf_hi(unsigned w) { return __uint_as_float(w & 0xffff0000u); }
; __device__ __forceinline__ f32x4 mfma16(bf16x8 a, bf16x8 b, f32x4 c) { return __builtin_amdgcn_mfma_f32_16x16x32_bf16(a, b, c, 0, 0, 0); }
; template <int NNT>
; __device__ __forceinline__ void part_sumsq(const f32x4 (&acc)[8][NNT], LAS float* part, int w, int fr, int fq) {
; #pragma unroll
;     for (int mt = 0; mt < 8; ++mt) { float s = 0.f;
; #pragma unroll
;         for (int nt = 0; nt < NNT; ++nt) s += (acc[mt][nt][0] * acc[mt][nt][0] + acc[mt][nt][1] * acc[mt][nt][1]) + (acc[mt][nt][2] * acc[mt][nt][2] + acc[mt][nt][3] * acc[mt][nt][3]);
;         s += __shfl_xor(s, 16); s += __shfl_xor(s, 32);
;         if (fq == 0) part[(16 * mt + fr) * 8 + w] = s; }
; }
; __device__ __forceinline__ void mixer_chunk(KP p, LAS unsigned char* lds, int l, int chunk) {
;     ...
; #pragma unroll
;         for (int mp = 0; mp < 4; ++mp) {
;             u32x4 wf[8];
; #pragma unroll
;             for (int q = 0; q < 2; ++q)
; #pragma unroll
;                 for (int ks = 0; ks < 4; ++ks) wf[4 * q + ks] = *(const u32x4*)(gwp + (size_t)(16 * (2 * mp + q)) * 128 + 32 * (ks <= mp ? ks : 0));
;             pin(wf);
; #pragma unroll
;             for (int q = 0; q < 2; ++q)
; #pragma unroll
;                 for (int n = 0; n < 2; ++n) { f32x4 a = (f32x4){0.f, 0.f, 0.f, 0.f};
; #pragma unroll
;                     for (int ks = 0; ks < 4; ++ks) if (ks <= mp) a = mfma16(vf[n][ks], as_bf16x8(wf[4 * q + ks]), a);
;                     const int mt = 2 * mp + q; const u32x2 u2 = uu[2 * mt + n]; const float bs_ = bias[mt];
;                     a[0] = bf_lo(u2.x) * (a[0] + bs_); a[1] = bf_hi(u2.x) * (a[1] + bs_); a[2] = bf_lo(u2.y) * (a[2] + bs_); a[3] = bf_hi(u2.y) * (a[3] + bs_);
;                     acc[mt][n] = a; }
;         }
;         part_sumsq<2>(acc, part0, w, fr, fq);
	s_nop 0
	v_mfma_f32_16x16x32_bf16 v[50:53], v[30:33], v[34:37], 0
	v_mfma_f32_16x16x32_bf16 v[34:37], v[14:17], v[34:37], 0
	s_waitcnt lgkmcnt(2)
	v_mfma_f32_16x16x32_bf16 v[70:73], v[2:5], v[38:41], v[34:37]
	v_mfma_f32_16x16x32_bf16 v[34:37], v[30:33], v[42:45], 0
	v_mfma_f32_16x16x32_bf16 v[78:81], v[26:29], v[38:41], v[50:53]
	v_mfma_f32_16x16x32_bf16 v[62:65], v[26:29], v[46:49], v[34:37]
	s_nop 1
	v_add_co_u32_e32 v50, vcc, s6, v126
	s_movk_i32 s6, 0x7000
	v_mfma_f32_16x16x32_bf16 v[34:37], v[14:17], v[42:45], 0
	v_addc_co_u32_e32 v51, vcc, 0, v127, vcc
	v_add_co_u32_e32 v154, vcc, s59, v126
	v_mfma_f32_16x16x32_bf16 v[54:57], v[2:5], v[46:49], v[34:37]
	s_nop 0
	v_addc_co_u32_e32 v155, vcc, 0, v127, vcc
	s_nop 2
	global_load_dwordx4 v[34:37], v[142:143], off
	global_load_dwordx4 v[38:41], v[142:143], off offset:64
	global_load_dwordx4 v[42:45], v[142:143], off offset:128
	global_load_dwordx4 v[46:49], v[154:155], off offset:-4096
	s_nop 0
	global_load_dwordx4 v[142:145], v[50:51], off offset:64
	global_load_dwordx4 v[146:149], v[50:51], off offset:128
	s_waitcnt vmcnt(5)
	v_mov_b64_e32 v[52:53], v[36:37]
	s_waitcnt vmcnt(2)
	v_mov_b64_e32 v[152:153], v[48:49]
	v_mov_b64_e32 v[50:51], v[34:35]
	v_mov_b64_e32 v[150:151], v[46:47]
	s_waitcnt vmcnt(0)
	s_nop 0
	v_mfma_f32_16x16x32_bf16 v[34:37], v[30:33], v[50:53], 0
	v_mfma_f32_16x16x32_bf16 v[34:37], v[26:29], v[38:41], v[34:37]
	v_mfma_f32_16x16x32_bf16 v[58:61], v[22:25], v[42:45], v[34:37]
	v_mfma_f32_16x16x32_bf16 v[34:37], v[14:17], v[50:53], 0
	v_mfma_f32_16x16x32_bf16 v[34:37], v[2:5], v[38:41], v[34:37]
	s_waitcnt lgkmcnt(1)
	v_mfma_f32_16x16x32_bf16 v[50:53], v[6:9], v[42:45], v[34:37]
	v_mfma_f32_16x16x32_bf16 v[34:37], v[30:33], v[150:153], 0
	v_mfma_f32_16x16x32_bf16 v[34:37], v[26:29], v[142:145], v[34:37]
	v_mfma_f32_16x16x32_bf16 v[46:49], v[22:25], v[146:149], v[34:37]
	v_mfma_f32_16x16x32_bf16 v[34:37], v[14:17], v[150:153], 0
	v_mfma_f32_16x16x32_bf16 v[34:37], v[2:5], v[142:145], v[34:37]
	v_mfma_f32_16x16x32_bf16 v[38:41], v[6:9], v[146:149], v[34:37]
	global_load_dwordx4 v[42:45], v[154:155], off
	global_load_dwordx4 v[142:145], v[154:155], off offset:64
	global_load_dwordx4 v[146:149], v[154:155], off offset:128
	global_load_dwordx4 v[150:153], v[154:155], off offset:192
	s_nop 2
	v_add_co_u32_e32 v34, vcc, s6, v126
	s_nop 1
	v_addc_co_u32_e32 v35, vcc, 0, v127, vcc
	global_load_dwordx4 v[154:157], v[34:35], off
	global_load_dwordx4 v[158:161], v[34:35], off offset:64
	global_load_dwordx4 v[168:171], v[34:35], off offset:128
	global_load_dwordx4 v[172:175], v[34:35], off offset:192
	s_waitcnt vmcnt(0)
	s_nop 0
	v_mfma_f32_16x16x32_bf16 v[34:37], v[30:33], v[42:45], 0
	v_mfma_f32_16x16x32_bf16 v[42:45], v[14:17], v[42:45], 0
	v_mfma_f32_16x16x32_bf16 v[14:17], v[14:17], v[154:157], 0
	v_mfma_f32_16x16x32_bf16 v[42:45], v[2:5], v[142:145], v[42:45]
	v_mfma_f32_16x16x32_bf16 v[2:5], v[2:5], v[158:161], v[14:17]
	v_mfma_f32_16x16x32_bf16 v[42:45], v[6:9], v[146:149], v[42:45]
	v_mfma_f32_16x16x32_bf16 v[2:5], v[6:9], v[168:171], v[2:5]
	v_mul_f32_e32 v6, v135, v135
	v_mul_f32_e32 v7, v137, v137
	v_fmac_f32_e32 v6, v0, v0
	v_mfma_f32_16x16x32_bf16 v[30:33], v[30:33], v[154:157], 0
	v_fmac_f32_e32 v7, v136, v136
	v_add_f32_e32 v6, v6, v7
	v_mul_f32_e32 v7, v139, v139
	v_mul_f32_e32 v8, v141, v141
	v_fmac_f32_e32 v7, v138, v138
	v_fmac_f32_e32 v8, v140, v140
	v_add_f32_e32 v7, v7, v8
	v_mfma_f32_16x16x32_bf16 v[34:37], v[26:29], v[142:145], v[34:37]
	v_add_f32_e32 v6, v6, v7
	ds_bpermute_b32 v7, v207, v6
	s_waitcnt lgkmcnt(0)
	v_add_f32_e32 v6, v6, v7
	v_mfma_f32_16x16x32_bf16 v[26:29], v[26:29], v[158:161], v[30:33]
	ds_bpermute_b32 v7, v208, v6
	v_mfma_f32_16x16x32_bf16 v[34:37], v[22:25], v[146:149], v[34:37]
	v_mfma_f32_16x16x32_bf16 v[22:25], v[22:25], v[168:171], v[26:29]
	v_mfma_f32_16x16x32_bf16 v[34:37], v[18:21], v[150:153], v[34:37]
	v_mfma_f32_16x16x32_bf16 v[42:45], v[10:13], v[150:153], v[42:45]
	v_mfma_f32_16x16x32_bf16 v[18:21], v[18:21], v[172:175], v[22:25]
	v_mfma_f32_16x16x32_bf16 v[2:5], v[10:13], v[172:175], v[2:5]
	s_and_saveexec_b64 s[6:7], s[40:41]
	s_cbranch_execz .LBB0_420
	s_waitcnt lgkmcnt(0)
	v_add_f32_e32 v6, v6, v7
	ds_write_b32 v216, v6
